# adds: first K-loop iteration of every GEMM tile peeled with C=0 on first-touch MFMAs (no 128 v_mov accumulator zeroing per tile)
# speedup vs baseline: 1.0072x; 1.0031x over previous
.LBB0_372:
	s_ashr_i32 s21, s20, 31
	s_lshl_b64 s[22:23], s[20:21], 19
	s_add_u32 s22, s96, s22
	s_addc_u32 s23, s97, s23
	s_and_b64 s[24:25], s[4:5], exec
	s_cselect_b32 s21, s23, s29
	s_cselect_b32 s27, s22, s28
	s_ashr_i32 s13, s12, 31
	s_lshl_b64 s[24:25], s[12:13], 19
	s_add_u32 s24, s14, s24
	s_addc_u32 s25, s15, s25
	s_and_b64 s[36:37], s[4:5], exec
	s_cselect_b32 s13, s25, s31
	s_cselect_b32 s48, s24, s30
	s_add_u32 s49, s30, 0x100
	s_addc_u32 s50, s31, 0
	s_mov_b32 s51, -2
	ds_read_b128 v[150:153], v180
	ds_read_b128 v[154:157], v180 offset:1024
	ds_read_b128 v[158:161], v180 offset:2048
	ds_read_b128 v[162:165], v180 offset:3072
	ds_read_b128 v[184:187], v181
	ds_read_b128 v[188:191], v181 offset:1024
	ds_read_b128 v[192:195], v181 offset:2048
	ds_read_b128 v[196:199], v181 offset:3072
	s_add_u32 s30, s28, 0x100
	s_addc_u32 s31, s29, 0
	s_cmp_eq_u32 s51, 12
	s_cselect_b32 s39, s21, s31
	s_cselect_b32 s38, s27, s30
	s_cselect_b32 s37, s13, s50
	s_cselect_b32 s36, s48, s49
	v_lshl_add_u64 v[166:167], s[28:29], 0, v[142:143]
	s_add_i32 m0, s17, 0xc000
	ds_read_b128 v[200:203], v182
	ds_read_b128 v[204:207], v182 offset:1024
	ds_read_b128 v[208:211], v182 offset:2048
	ds_read_b128 v[212:215], v182 offset:3072
	ds_read_b128 v[216:219], v182 offset:4096
	ds_read_b128 v[220:223], v182 offset:5120
	ds_read_b128 v[224:227], v182 offset:6144
	ds_read_b128 v[228:231], v182 offset:7168
	global_load_lds_dwordx4 v[166:167], off
	v_lshl_add_u64 v[166:167], s[28:29], 0, v[144:145]
	s_add_i32 m0, s17, 0xe000
	s_nop 0
	global_load_lds_dwordx4 v[166:167], off
	s_waitcnt vmcnt(8)
	s_waitcnt lgkmcnt(0)
	s_barrier
	s_setprio 1
	s_waitcnt lgkmcnt(0)
	v_mfma_f32_16x16x32_bf16 v[82:85], v[150:153], v[200:203], 0
	v_mfma_f32_16x16x32_bf16 v[78:81], v[158:161], v[200:203], 0
	v_mfma_f32_16x16x32_bf16 v[70:73], v[150:153], v[208:211], 0
	v_mfma_f32_16x16x32_bf16 v[66:69], v[158:161], v[208:211], 0
	v_mfma_f32_16x16x32_bf16 v[62:65], v[150:153], v[216:219], 0
	v_mfma_f32_16x16x32_bf16 v[58:61], v[158:161], v[216:219], 0
	v_mfma_f32_16x16x32_bf16 v[54:57], v[150:153], v[224:227], 0
	v_mfma_f32_16x16x32_bf16 v[50:53], v[158:161], v[224:227], 0
	v_mfma_f32_16x16x32_bf16 v[82:85], v[154:157], v[204:207], v[82:85]
	v_mfma_f32_16x16x32_bf16 v[78:81], v[162:165], v[204:207], v[78:81]
	v_mfma_f32_16x16x32_bf16 v[70:73], v[154:157], v[212:215], v[70:73]
	v_mfma_f32_16x16x32_bf16 v[66:69], v[162:165], v[212:215], v[66:69]
	v_mfma_f32_16x16x32_bf16 v[62:65], v[154:157], v[220:223], v[62:65]
	v_mfma_f32_16x16x32_bf16 v[58:61], v[162:165], v[220:223], v[58:61]
	v_mfma_f32_16x16x32_bf16 v[54:57], v[154:157], v[228:231], v[54:57]
	v_mfma_f32_16x16x32_bf16 v[50:53], v[162:165], v[228:231], v[50:53]
	s_setprio 0
	s_setprio 1
	v_mfma_f32_16x16x32_bf16 v[126:129], v[184:187], v[200:203], 0
	v_mfma_f32_16x16x32_bf16 v[122:125], v[192:195], v[200:203], 0
	v_mfma_f32_16x16x32_bf16 v[118:121], v[184:187], v[208:211], 0
	v_mfma_f32_16x16x32_bf16 v[114:117], v[192:195], v[208:211], 0
	v_mfma_f32_16x16x32_bf16 v[110:113], v[184:187], v[216:219], 0
	v_mfma_f32_16x16x32_bf16 v[106:109], v[192:195], v[216:219], 0
	v_mfma_f32_16x16x32_bf16 v[102:105], v[184:187], v[224:227], 0
	v_mfma_f32_16x16x32_bf16 v[98:101], v[192:195], v[224:227], 0
	v_mfma_f32_16x16x32_bf16 v[126:129], v[188:191], v[204:207], v[126:129]
	v_mfma_f32_16x16x32_bf16 v[122:125], v[196:199], v[204:207], v[122:125]
	v_mfma_f32_16x16x32_bf16 v[118:121], v[188:191], v[212:215], v[118:121]
	v_mfma_f32_16x16x32_bf16 v[114:117], v[196:199], v[212:215], v[114:117]
	v_mfma_f32_16x16x32_bf16 v[110:113], v[188:191], v[220:223], v[110:113]
	v_mfma_f32_16x16x32_bf16 v[106:109], v[196:199], v[220:223], v[106:109]
	v_mfma_f32_16x16x32_bf16 v[102:105], v[188:191], v[228:231], v[102:105]
	v_mfma_f32_16x16x32_bf16 v[98:101], v[196:199], v[228:231], v[98:101]
	s_setprio 0
	s_barrier
	s_add_i32 s28, s45, s16
	v_lshl_add_u64 v[166:167], s[36:37], 0, v[134:135]
	s_mov_b32 m0, s28
	ds_read_b128 v[200:203], v182 offset:16384
	ds_read_b128 v[204:207], v182 offset:17408
	ds_read_b128 v[208:211], v182 offset:18432
	ds_read_b128 v[212:215], v182 offset:19456
	ds_read_b128 v[216:219], v182 offset:20480
	ds_read_b128 v[220:223], v182 offset:21504
	ds_read_b128 v[224:227], v182 offset:22528
	ds_read_b128 v[228:231], v182 offset:23552
	global_load_lds_dwordx4 v[166:167], off
	s_add_i32 m0, s28, 0x2000
	s_add_u32 s28, s36, 0x40000
	v_lshl_add_u64 v[232:233], s[36:37], 0, v[136:137]
	s_addc_u32 s29, s37, 0
	s_add_i32 s52, s46, s16
	global_load_lds_dwordx4 v[232:233], off
	v_lshl_add_u64 v[234:235], s[28:29], 0, v[134:135]
	s_mov_b32 m0, s52
	v_lshl_add_u64 v[236:237], s[38:39], 0, v[130:131]
	global_load_lds_dwordx4 v[234:235], off
	v_lshl_add_u64 v[234:235], s[28:29], 0, v[136:137]
	s_add_i32 m0, s52, 0x2000
	s_nop 0
	global_load_lds_dwordx4 v[234:235], off
	v_lshl_add_u64 v[234:235], s[38:39], 0, v[132:133]
	s_mov_b32 m0, s17
	s_nop 0
	global_load_lds_dwordx4 v[234:235], off
	s_mov_b32 m0, s34
	s_nop 0
	global_load_lds_dwordx4 v[236:237], off
	s_waitcnt vmcnt(8)
	s_waitcnt lgkmcnt(0)
	s_barrier
	s_setprio 1
	s_waitcnt lgkmcnt(0)
	v_mfma_f32_16x16x32_bf16 v[38:41], v[150:153], v[200:203], 0
	v_mfma_f32_16x16x32_bf16 v[34:37], v[158:161], v[200:203], 0
	v_mfma_f32_16x16x32_bf16 v[26:29], v[150:153], v[208:211], 0
	v_mfma_f32_16x16x32_bf16 v[22:25], v[158:161], v[208:211], 0
	v_mfma_f32_16x16x32_bf16 v[14:17], v[150:153], v[216:219], 0
	v_mfma_f32_16x16x32_bf16 v[10:13], v[158:161], v[216:219], 0
	v_mfma_f32_16x16x32_bf16 v[6:9], v[150:153], v[224:227], 0
	v_mfma_f32_16x16x32_bf16 v[2:5], v[158:161], v[224:227], 0
	v_mfma_f32_16x16x32_bf16 v[38:41], v[154:157], v[204:207], v[38:41]
	v_mfma_f32_16x16x32_bf16 v[34:37], v[162:165], v[204:207], v[34:37]
	v_mfma_f32_16x16x32_bf16 v[26:29], v[154:157], v[212:215], v[26:29]
	v_mfma_f32_16x16x32_bf16 v[22:25], v[162:165], v[212:215], v[22:25]
	v_mfma_f32_16x16x32_bf16 v[14:17], v[154:157], v[220:223], v[14:17]
	v_mfma_f32_16x16x32_bf16 v[10:13], v[162:165], v[220:223], v[10:13]
	v_mfma_f32_16x16x32_bf16 v[6:9], v[154:157], v[228:231], v[6:9]
	v_mfma_f32_16x16x32_bf16 v[2:5], v[162:165], v[228:231], v[2:5]
	s_setprio 0
	s_setprio 1
	v_mfma_f32_16x16x32_bf16 v[94:97], v[184:187], v[200:203], 0
	v_mfma_f32_16x16x32_bf16 v[90:93], v[192:195], v[200:203], 0
	v_mfma_f32_16x16x32_bf16 v[86:89], v[184:187], v[208:211], 0
	v_mfma_f32_16x16x32_bf16 v[74:77], v[192:195], v[208:211], 0
	v_mfma_f32_16x16x32_bf16 v[46:49], v[184:187], v[216:219], 0
	v_mfma_f32_16x16x32_bf16 v[42:45], v[192:195], v[216:219], 0
	v_mfma_f32_16x16x32_bf16 v[30:33], v[184:187], v[224:227], 0
	v_mfma_f32_16x16x32_bf16 v[18:21], v[192:195], v[224:227], 0
	v_mfma_f32_16x16x32_bf16 v[94:97], v[188:191], v[204:207], v[94:97]
	v_mfma_f32_16x16x32_bf16 v[90:93], v[196:199], v[204:207], v[90:93]
	v_mfma_f32_16x16x32_bf16 v[86:89], v[188:191], v[212:215], v[86:89]
	v_mfma_f32_16x16x32_bf16 v[74:77], v[196:199], v[212:215], v[74:77]
	v_mfma_f32_16x16x32_bf16 v[46:49], v[188:191], v[220:223], v[46:49]
	v_mfma_f32_16x16x32_bf16 v[42:45], v[196:199], v[220:223], v[42:45]
	v_mfma_f32_16x16x32_bf16 v[30:33], v[188:191], v[228:231], v[30:33]
	v_mfma_f32_16x16x32_bf16 v[18:21], v[196:199], v[228:231], v[18:21]
	s_setprio 0
	s_barrier
	s_add_i32 s52, 0, 0x18000
	v_add_u32_e32 v138, s52, v178
	s_add_i32 s53, 0, 0x1c000
	ds_read_b128 v[150:153], v138
	ds_read_b128 v[154:157], v138 offset:1024
	ds_read_b128 v[158:161], v138 offset:2048
	ds_read_b128 v[162:165], v138 offset:3072
	v_add_u32_e32 v138, s53, v178
	ds_read_b128 v[184:187], v138
	ds_read_b128 v[188:191], v138 offset:1024
	ds_read_b128 v[192:195], v138 offset:2048
	ds_read_b128 v[196:199], v138 offset:3072
	s_add_u32 s28, s38, 0x40000
	s_addc_u32 s29, s39, 0
	s_mov_b32 m0, s35
	v_lshl_add_u64 v[238:239], s[28:29], 0, v[132:133]
	ds_read_b128 v[200:203], v182 offset:32768
	ds_read_b128 v[204:207], v182 offset:33792
	ds_read_b128 v[208:211], v182 offset:34816
	ds_read_b128 v[212:215], v182 offset:35840
	ds_read_b128 v[216:219], v182 offset:36864
	ds_read_b128 v[220:223], v182 offset:37888
	ds_read_b128 v[224:227], v182 offset:38912
	ds_read_b128 v[228:231], v182 offset:39936
	global_load_lds_dwordx4 v[238:239], off
	v_lshl_add_u64 v[238:239], s[28:29], 0, v[130:131]
	s_mov_b32 m0, s40
	s_nop 0
	global_load_lds_dwordx4 v[238:239], off
	s_waitcnt vmcnt(8)
	s_waitcnt lgkmcnt(0)
	s_barrier
	s_setprio 1
	s_waitcnt lgkmcnt(0)
	v_mfma_f32_16x16x32_bf16 v[82:85], v[150:153], v[200:203], v[82:85]
	v_mfma_f32_16x16x32_bf16 v[78:81], v[158:161], v[200:203], v[78:81]
	v_mfma_f32_16x16x32_bf16 v[70:73], v[150:153], v[208:211], v[70:73]
	v_mfma_f32_16x16x32_bf16 v[66:69], v[158:161], v[208:211], v[66:69]
	v_mfma_f32_16x16x32_bf16 v[62:65], v[150:153], v[216:219], v[62:65]
	v_mfma_f32_16x16x32_bf16 v[58:61], v[158:161], v[216:219], v[58:61]
	v_mfma_f32_16x16x32_bf16 v[54:57], v[150:153], v[224:227], v[54:57]
	v_mfma_f32_16x16x32_bf16 v[50:53], v[158:161], v[224:227], v[50:53]
	v_mfma_f32_16x16x32_bf16 v[82:85], v[154:157], v[204:207], v[82:85]
	v_mfma_f32_16x16x32_bf16 v[78:81], v[162:165], v[204:207], v[78:81]
	v_mfma_f32_16x16x32_bf16 v[70:73], v[154:157], v[212:215], v[70:73]
	v_mfma_f32_16x16x32_bf16 v[66:69], v[162:165], v[212:215], v[66:69]
	v_mfma_f32_16x16x32_bf16 v[62:65], v[154:157], v[220:223], v[62:65]
	v_mfma_f32_16x16x32_bf16 v[58:61], v[162:165], v[220:223], v[58:61]
	v_mfma_f32_16x16x32_bf16 v[54:57], v[154:157], v[228:231], v[54:57]
	v_mfma_f32_16x16x32_bf16 v[50:53], v[162:165], v[228:231], v[50:53]
	s_setprio 0
	s_setprio 1
	v_mfma_f32_16x16x32_bf16 v[126:129], v[184:187], v[200:203], v[126:129]
	v_mfma_f32_16x16x32_bf16 v[122:125], v[192:195], v[200:203], v[122:125]
	v_mfma_f32_16x16x32_bf16 v[118:121], v[184:187], v[208:211], v[118:121]
	v_mfma_f32_16x16x32_bf16 v[114:117], v[192:195], v[208:211], v[114:117]
	v_mfma_f32_16x16x32_bf16 v[110:113], v[184:187], v[216:219], v[110:113]
	v_mfma_f32_16x16x32_bf16 v[106:109], v[192:195], v[216:219], v[106:109]
	v_mfma_f32_16x16x32_bf16 v[102:105], v[184:187], v[224:227], v[102:105]
	v_mfma_f32_16x16x32_bf16 v[98:101], v[192:195], v[224:227], v[98:101]
	v_mfma_f32_16x16x32_bf16 v[126:129], v[188:191], v[204:207], v[126:129]
	v_mfma_f32_16x16x32_bf16 v[122:125], v[196:199], v[204:207], v[122:125]
	v_mfma_f32_16x16x32_bf16 v[118:121], v[188:191], v[212:215], v[118:121]
	v_mfma_f32_16x16x32_bf16 v[114:117], v[196:199], v[212:215], v[114:117]
	v_mfma_f32_16x16x32_bf16 v[110:113], v[188:191], v[220:223], v[110:113]
	v_mfma_f32_16x16x32_bf16 v[106:109], v[196:199], v[220:223], v[106:109]
	v_mfma_f32_16x16x32_bf16 v[102:105], v[188:191], v[228:231], v[102:105]
	v_mfma_f32_16x16x32_bf16 v[98:101], v[196:199], v[228:231], v[98:101]
	s_setprio 0
	s_barrier
	s_add_i32 s28, s52, s16
	v_lshl_add_u64 v[166:167], v[166:167], 0, s[6:7]
	s_mov_b32 m0, s28
	ds_read_b128 v[200:203], v182 offset:49152
	ds_read_b128 v[204:207], v182 offset:50176
	ds_read_b128 v[208:211], v182 offset:51200
	ds_read_b128 v[212:215], v182 offset:52224
	ds_read_b128 v[216:219], v182 offset:53248
	ds_read_b128 v[220:223], v182 offset:54272
	ds_read_b128 v[224:227], v182 offset:55296
	ds_read_b128 v[228:231], v182 offset:56320
	global_load_lds_dwordx4 v[166:167], off
	s_add_i32 m0, s28, 0x2000
	s_add_u32 s28, s36, 0x40080
	v_lshl_add_u64 v[166:167], v[232:233], 0, s[6:7]
	s_addc_u32 s29, s37, 0
	s_add_i32 s36, s53, s16
	global_load_lds_dwordx4 v[166:167], off
	v_lshl_add_u64 v[166:167], s[28:29], 0, v[134:135]
	s_mov_b32 m0, s36
	s_nop 0
	global_load_lds_dwordx4 v[166:167], off
	v_lshl_add_u64 v[166:167], s[28:29], 0, v[136:137]
	s_add_i32 m0, s36, 0x2000
	s_nop 0
	global_load_lds_dwordx4 v[166:167], off
	v_lshl_add_u64 v[166:167], v[234:235], 0, s[6:7]
	s_mov_b32 m0, s42
	s_nop 0
	global_load_lds_dwordx4 v[166:167], off
	v_lshl_add_u64 v[166:167], v[236:237], 0, s[6:7]
	s_mov_b32 m0, s43
	s_nop 0
	global_load_lds_dwordx4 v[166:167], off
	s_waitcnt vmcnt(8)
	s_waitcnt lgkmcnt(0)
	s_barrier
	s_setprio 1
	s_waitcnt lgkmcnt(0)
	v_mfma_f32_16x16x32_bf16 v[38:41], v[150:153], v[200:203], v[38:41]
	v_mfma_f32_16x16x32_bf16 v[34:37], v[158:161], v[200:203], v[34:37]
	v_mfma_f32_16x16x32_bf16 v[26:29], v[150:153], v[208:211], v[26:29]
	v_mfma_f32_16x16x32_bf16 v[22:25], v[158:161], v[208:211], v[22:25]
	v_mfma_f32_16x16x32_bf16 v[14:17], v[150:153], v[216:219], v[14:17]
	v_mfma_f32_16x16x32_bf16 v[10:13], v[158:161], v[216:219], v[10:13]
	v_mfma_f32_16x16x32_bf16 v[6:9], v[150:153], v[224:227], v[6:9]
	v_mfma_f32_16x16x32_bf16 v[2:5], v[158:161], v[224:227], v[2:5]
	v_mfma_f32_16x16x32_bf16 v[38:41], v[154:157], v[204:207], v[38:41]
	v_mfma_f32_16x16x32_bf16 v[34:37], v[162:165], v[204:207], v[34:37]
	v_mfma_f32_16x16x32_bf16 v[26:29], v[154:157], v[212:215], v[26:29]
	v_mfma_f32_16x16x32_bf16 v[22:25], v[162:165], v[212:215], v[22:25]
	v_mfma_f32_16x16x32_bf16 v[14:17], v[154:157], v[220:223], v[14:17]
	v_mfma_f32_16x16x32_bf16 v[10:13], v[162:165], v[220:223], v[10:13]
	v_mfma_f32_16x16x32_bf16 v[6:9], v[154:157], v[228:231], v[6:9]
	v_mfma_f32_16x16x32_bf16 v[2:5], v[162:165], v[228:231], v[2:5]
	s_setprio 0
	s_setprio 1
	v_mfma_f32_16x16x32_bf16 v[94:97], v[184:187], v[200:203], v[94:97]
	v_mfma_f32_16x16x32_bf16 v[90:93], v[192:195], v[200:203], v[90:93]
	v_mfma_f32_16x16x32_bf16 v[86:89], v[184:187], v[208:211], v[86:89]
	v_mfma_f32_16x16x32_bf16 v[74:77], v[192:195], v[208:211], v[74:77]
	v_mfma_f32_16x16x32_bf16 v[46:49], v[184:187], v[216:219], v[46:49]
	v_mfma_f32_16x16x32_bf16 v[42:45], v[192:195], v[216:219], v[42:45]
	v_mfma_f32_16x16x32_bf16 v[30:33], v[184:187], v[224:227], v[30:33]
	v_mfma_f32_16x16x32_bf16 v[18:21], v[192:195], v[224:227], v[18:21]
	v_mfma_f32_16x16x32_bf16 v[94:97], v[188:191], v[204:207], v[94:97]
	v_mfma_f32_16x16x32_bf16 v[90:93], v[196:199], v[204:207], v[90:93]
	v_mfma_f32_16x16x32_bf16 v[86:89], v[188:191], v[212:215], v[86:89]
	v_mfma_f32_16x16x32_bf16 v[74:77], v[196:199], v[212:215], v[74:77]
	v_mfma_f32_16x16x32_bf16 v[46:49], v[188:191], v[220:223], v[46:49]
	v_mfma_f32_16x16x32_bf16 v[42:45], v[196:199], v[220:223], v[42:45]
	v_mfma_f32_16x16x32_bf16 v[30:33], v[188:191], v[228:231], v[30:33]
	v_mfma_f32_16x16x32_bf16 v[18:21], v[196:199], v[228:231], v[18:21]
	s_setprio 0
	s_barrier
	s_add_i32 s51, s51, 2
	s_add_u32 s49, s49, 0x100
	s_addc_u32 s50, s50, 0
	s_cmp_gt_u32 s51, 13
	s_mov_b64 s[28:29], s[30:31]
	s_cbranch_scc0 .LBB0_373
	s_branch .Lpeel_exit_373

.Lpeel_exit_373:
	s_and_b64 vcc, exec, s[8:9]
	s_cbranch_vccz .LBB0_376
	s_barrier

.LBB0_404:
	s_ashr_i32 s29, s28, 31
	s_lshl_b64 s[30:31], s[28:29], 19
	s_add_u32 s30, s14, s30
	s_addc_u32 s31, s15, s31
	s_and_b64 s[34:35], s[24:25], exec
	s_cselect_b32 s5, s31, s41
	s_cselect_b32 s29, s30, s40
	s_ashr_i32 s27, s26, 31
	s_lshl_b64 s[34:35], s[26:27], 19
	s_add_u32 s36, s16, s34
	s_addc_u32 s37, s17, s35
	s_and_b64 s[34:35], s[24:25], exec
	s_cselect_b32 s27, s37, s43
	s_cselect_b32 s34, s36, s42
	s_add_u32 s35, s42, 0x100
	s_addc_u32 s39, s43, 0
	s_mov_b32 s61, -2
	ds_read_b128 v[140:143], v156
	ds_read_b128 v[144:147], v156 offset:1024
	ds_read_b128 v[148:151], v156 offset:2048
	ds_read_b128 v[164:167], v156 offset:3072
	ds_read_b128 v[168:171], v157
	ds_read_b128 v[178:181], v157 offset:1024
	ds_read_b128 v[182:185], v157 offset:2048
	ds_read_b128 v[186:189], v157 offset:3072
	s_add_u32 s42, s40, 0x100
	s_addc_u32 s43, s41, 0
	s_cmp_eq_u32 s61, 12
	s_cselect_b32 s47, s5, s43
	s_cselect_b32 s46, s29, s42
	s_cselect_b32 s45, s27, s39
	s_cselect_b32 s44, s34, s35
	v_lshl_add_u64 v[152:153], s[40:41], 0, v[136:137]
	s_add_i32 m0, s49, 0xc000
	ds_read_b128 v[190:193], v158
	ds_read_b128 v[194:197], v158 offset:1024
	ds_read_b128 v[198:201], v158 offset:2048
	ds_read_b128 v[202:205], v158 offset:3072
	ds_read_b128 v[206:209], v158 offset:4096
	ds_read_b128 v[210:213], v158 offset:5120
	ds_read_b128 v[214:217], v158 offset:6144
	ds_read_b128 v[218:221], v158 offset:7168
	global_load_lds_dwordx4 v[152:153], off
	v_lshl_add_u64 v[152:153], s[40:41], 0, v[138:139]
	s_add_i32 m0, s49, 0xe000
	s_nop 0
	global_load_lds_dwordx4 v[152:153], off
	s_waitcnt vmcnt(8)
	s_waitcnt lgkmcnt(0)
	s_barrier
	s_setprio 1
	s_waitcnt lgkmcnt(0)
	v_mfma_f32_16x16x32_bf16 v[126:129], v[140:143], v[190:193], 0
	v_mfma_f32_16x16x32_bf16 v[122:125], v[148:151], v[190:193], 0
	v_mfma_f32_16x16x32_bf16 v[110:113], v[140:143], v[198:201], 0
	v_mfma_f32_16x16x32_bf16 v[106:109], v[148:151], v[198:201], 0
	v_mfma_f32_16x16x32_bf16 v[94:97], v[140:143], v[206:209], 0
	v_mfma_f32_16x16x32_bf16 v[90:93], v[148:151], v[206:209], 0
	v_mfma_f32_16x16x32_bf16 v[78:81], v[140:143], v[214:217], 0
	v_mfma_f32_16x16x32_bf16 v[74:77], v[148:151], v[214:217], 0
	v_mfma_f32_16x16x32_bf16 v[126:129], v[144:147], v[194:197], v[126:129]
	v_mfma_f32_16x16x32_bf16 v[122:125], v[164:167], v[194:197], v[122:125]
	v_mfma_f32_16x16x32_bf16 v[110:113], v[144:147], v[202:205], v[110:113]
	v_mfma_f32_16x16x32_bf16 v[106:109], v[164:167], v[202:205], v[106:109]
	v_mfma_f32_16x16x32_bf16 v[94:97], v[144:147], v[210:213], v[94:97]
	v_mfma_f32_16x16x32_bf16 v[90:93], v[164:167], v[210:213], v[90:93]
	v_mfma_f32_16x16x32_bf16 v[78:81], v[144:147], v[218:221], v[78:81]
	v_mfma_f32_16x16x32_bf16 v[74:77], v[164:167], v[218:221], v[74:77]
	s_setprio 0
	s_setprio 1
	v_mfma_f32_16x16x32_bf16 v[118:121], v[168:171], v[190:193], 0
	v_mfma_f32_16x16x32_bf16 v[114:117], v[182:185], v[190:193], 0
	v_mfma_f32_16x16x32_bf16 v[102:105], v[168:171], v[198:201], 0
	v_mfma_f32_16x16x32_bf16 v[98:101], v[182:185], v[198:201], 0
	v_mfma_f32_16x16x32_bf16 v[86:89], v[168:171], v[206:209], 0
	v_mfma_f32_16x16x32_bf16 v[82:85], v[182:185], v[206:209], 0
	v_mfma_f32_16x16x32_bf16 v[70:73], v[168:171], v[214:217], 0
	v_mfma_f32_16x16x32_bf16 v[66:69], v[182:185], v[214:217], 0
	v_mfma_f32_16x16x32_bf16 v[118:121], v[178:181], v[194:197], v[118:121]
	v_mfma_f32_16x16x32_bf16 v[114:117], v[186:189], v[194:197], v[114:117]
	v_mfma_f32_16x16x32_bf16 v[102:105], v[178:181], v[202:205], v[102:105]
	v_mfma_f32_16x16x32_bf16 v[98:101], v[186:189], v[202:205], v[98:101]
	v_mfma_f32_16x16x32_bf16 v[86:89], v[178:181], v[210:213], v[86:89]
	v_mfma_f32_16x16x32_bf16 v[82:85], v[186:189], v[210:213], v[82:85]
	v_mfma_f32_16x16x32_bf16 v[70:73], v[178:181], v[218:221], v[70:73]
	v_mfma_f32_16x16x32_bf16 v[66:69], v[186:189], v[218:221], v[66:69]
	s_setprio 0
	s_barrier
	s_add_i32 s40, s59, s48
	v_lshl_add_u64 v[152:153], s[44:45], 0, v[132:133]
	s_mov_b32 m0, s40
	ds_read_b128 v[190:193], v158 offset:16384
	ds_read_b128 v[194:197], v158 offset:17408
	ds_read_b128 v[198:201], v158 offset:18432
	ds_read_b128 v[202:205], v158 offset:19456
	ds_read_b128 v[206:209], v158 offset:20480
	ds_read_b128 v[210:213], v158 offset:21504
	ds_read_b128 v[214:217], v158 offset:22528
	ds_read_b128 v[218:221], v158 offset:23552
	global_load_lds_dwordx4 v[152:153], off
	s_add_i32 m0, s40, 0x2000
	s_add_u32 s40, s44, 0x40000
	v_lshl_add_u64 v[172:173], s[44:45], 0, v[130:131]
	s_addc_u32 s41, s45, 0
	s_add_i32 s62, s60, s48
	global_load_lds_dwordx4 v[172:173], off
	v_lshl_add_u64 v[222:223], s[40:41], 0, v[132:133]
	s_mov_b32 m0, s62
	v_lshl_add_u64 v[224:225], s[46:47], 0, v[130:131]
	global_load_lds_dwordx4 v[222:223], off
	v_lshl_add_u64 v[222:223], s[40:41], 0, v[130:131]
	s_add_i32 m0, s62, 0x2000
	s_nop 0
	global_load_lds_dwordx4 v[222:223], off
	v_lshl_add_u64 v[222:223], s[46:47], 0, v[132:133]
	s_mov_b32 m0, s49
	s_nop 0
	global_load_lds_dwordx4 v[222:223], off
	s_mov_b32 m0, s50
	s_nop 0
	global_load_lds_dwordx4 v[224:225], off
	s_waitcnt vmcnt(8)
	s_waitcnt lgkmcnt(0)
	s_barrier
	s_setprio 1
	s_waitcnt lgkmcnt(0)
	v_mfma_f32_16x16x32_bf16 v[62:65], v[140:143], v[190:193], 0
	v_mfma_f32_16x16x32_bf16 v[58:61], v[148:151], v[190:193], 0
	v_mfma_f32_16x16x32_bf16 v[46:49], v[140:143], v[198:201], 0
	v_mfma_f32_16x16x32_bf16 v[42:45], v[148:151], v[198:201], 0
	v_mfma_f32_16x16x32_bf16 v[30:33], v[140:143], v[206:209], 0
	v_mfma_f32_16x16x32_bf16 v[26:29], v[148:151], v[206:209], 0
	v_mfma_f32_16x16x32_bf16 v[14:17], v[140:143], v[214:217], 0
	v_mfma_f32_16x16x32_bf16 v[10:13], v[148:151], v[214:217], 0
	v_mfma_f32_16x16x32_bf16 v[62:65], v[144:147], v[194:197], v[62:65]
	v_mfma_f32_16x16x32_bf16 v[58:61], v[164:167], v[194:197], v[58:61]
	v_mfma_f32_16x16x32_bf16 v[46:49], v[144:147], v[202:205], v[46:49]
	v_mfma_f32_16x16x32_bf16 v[42:45], v[164:167], v[202:205], v[42:45]
	v_mfma_f32_16x16x32_bf16 v[30:33], v[144:147], v[210:213], v[30:33]
	v_mfma_f32_16x16x32_bf16 v[26:29], v[164:167], v[210:213], v[26:29]
	v_mfma_f32_16x16x32_bf16 v[14:17], v[144:147], v[218:221], v[14:17]
	v_mfma_f32_16x16x32_bf16 v[10:13], v[164:167], v[218:221], v[10:13]
	s_setprio 0
	s_setprio 1
	v_mfma_f32_16x16x32_bf16 v[54:57], v[168:171], v[190:193], 0
	v_mfma_f32_16x16x32_bf16 v[50:53], v[182:185], v[190:193], 0
	v_mfma_f32_16x16x32_bf16 v[38:41], v[168:171], v[198:201], 0
	v_mfma_f32_16x16x32_bf16 v[34:37], v[182:185], v[198:201], 0
	v_mfma_f32_16x16x32_bf16 v[22:25], v[168:171], v[206:209], 0
	v_mfma_f32_16x16x32_bf16 v[18:21], v[182:185], v[206:209], 0
	v_mfma_f32_16x16x32_bf16 v[6:9], v[168:171], v[214:217], 0
	v_mfma_f32_16x16x32_bf16 v[2:5], v[182:185], v[214:217], 0
	v_mfma_f32_16x16x32_bf16 v[54:57], v[178:181], v[194:197], v[54:57]
	v_mfma_f32_16x16x32_bf16 v[50:53], v[186:189], v[194:197], v[50:53]
	v_mfma_f32_16x16x32_bf16 v[38:41], v[178:181], v[202:205], v[38:41]
	v_mfma_f32_16x16x32_bf16 v[34:37], v[186:189], v[202:205], v[34:37]
	v_mfma_f32_16x16x32_bf16 v[22:25], v[178:181], v[210:213], v[22:25]
	v_mfma_f32_16x16x32_bf16 v[18:21], v[186:189], v[210:213], v[18:21]
	v_mfma_f32_16x16x32_bf16 v[6:9], v[178:181], v[218:221], v[6:9]
	v_mfma_f32_16x16x32_bf16 v[2:5], v[186:189], v[218:221], v[2:5]
	s_setprio 0
	s_barrier
	s_add_i32 s62, 0, 0x18000
	v_add_u32_e32 v134, s62, v154
	s_add_i32 s63, 0, 0x1c000
	ds_read_b128 v[140:143], v134
	ds_read_b128 v[144:147], v134 offset:1024
	ds_read_b128 v[148:151], v134 offset:2048
	ds_read_b128 v[164:167], v134 offset:3072
	v_add_u32_e32 v134, s63, v154
	ds_read_b128 v[168:171], v134
	ds_read_b128 v[178:181], v134 offset:1024
	ds_read_b128 v[182:185], v134 offset:2048
	ds_read_b128 v[186:189], v134 offset:3072
	s_add_u32 s40, s46, 0x40000
	s_addc_u32 s41, s47, 0
	s_mov_b32 m0, s51
	v_lshl_add_u64 v[226:227], s[40:41], 0, v[132:133]
	ds_read_b128 v[190:193], v158 offset:32768
	ds_read_b128 v[194:197], v158 offset:33792
	ds_read_b128 v[198:201], v158 offset:34816
	ds_read_b128 v[202:205], v158 offset:35840
	ds_read_b128 v[206:209], v158 offset:36864
	ds_read_b128 v[210:213], v158 offset:37888
	ds_read_b128 v[214:217], v158 offset:38912
	ds_read_b128 v[218:221], v158 offset:39936
	global_load_lds_dwordx4 v[226:227], off
	v_lshl_add_u64 v[226:227], s[40:41], 0, v[130:131]
	s_mov_b32 m0, s52
	s_nop 0
	global_load_lds_dwordx4 v[226:227], off
	s_waitcnt vmcnt(8)
	s_waitcnt lgkmcnt(0)
	s_barrier
	s_setprio 1
	s_waitcnt lgkmcnt(0)
	v_mfma_f32_16x16x32_bf16 v[126:129], v[140:143], v[190:193], v[126:129]
	v_mfma_f32_16x16x32_bf16 v[122:125], v[148:151], v[190:193], v[122:125]
	v_mfma_f32_16x16x32_bf16 v[110:113], v[140:143], v[198:201], v[110:113]
	v_mfma_f32_16x16x32_bf16 v[106:109], v[148:151], v[198:201], v[106:109]
	v_mfma_f32_16x16x32_bf16 v[94:97], v[140:143], v[206:209], v[94:97]
	v_mfma_f32_16x16x32_bf16 v[90:93], v[148:151], v[206:209], v[90:93]
	v_mfma_f32_16x16x32_bf16 v[78:81], v[140:143], v[214:217], v[78:81]
	v_mfma_f32_16x16x32_bf16 v[74:77], v[148:151], v[214:217], v[74:77]
	v_mfma_f32_16x16x32_bf16 v[126:129], v[144:147], v[194:197], v[126:129]
	v_mfma_f32_16x16x32_bf16 v[122:125], v[164:167], v[194:197], v[122:125]
	v_mfma_f32_16x16x32_bf16 v[110:113], v[144:147], v[202:205], v[110:113]
	v_mfma_f32_16x16x32_bf16 v[106:109], v[164:167], v[202:205], v[106:109]
	v_mfma_f32_16x16x32_bf16 v[94:97], v[144:147], v[210:213], v[94:97]
	v_mfma_f32_16x16x32_bf16 v[90:93], v[164:167], v[210:213], v[90:93]
	v_mfma_f32_16x16x32_bf16 v[78:81], v[144:147], v[218:221], v[78:81]
	v_mfma_f32_16x16x32_bf16 v[74:77], v[164:167], v[218:221], v[74:77]
	s_setprio 0
	s_setprio 1
	v_mfma_f32_16x16x32_bf16 v[118:121], v[168:171], v[190:193], v[118:121]
	v_mfma_f32_16x16x32_bf16 v[114:117], v[182:185], v[190:193], v[114:117]
	v_mfma_f32_16x16x32_bf16 v[102:105], v[168:171], v[198:201], v[102:105]
	v_mfma_f32_16x16x32_bf16 v[98:101], v[182:185], v[198:201], v[98:101]
	v_mfma_f32_16x16x32_bf16 v[86:89], v[168:171], v[206:209], v[86:89]
	v_mfma_f32_16x16x32_bf16 v[82:85], v[182:185], v[206:209], v[82:85]
	v_mfma_f32_16x16x32_bf16 v[70:73], v[168:171], v[214:217], v[70:73]
	v_mfma_f32_16x16x32_bf16 v[66:69], v[182:185], v[214:217], v[66:69]
	v_mfma_f32_16x16x32_bf16 v[118:121], v[178:181], v[194:197], v[118:121]
	v_mfma_f32_16x16x32_bf16 v[114:117], v[186:189], v[194:197], v[114:117]
	v_mfma_f32_16x16x32_bf16 v[102:105], v[178:181], v[202:205], v[102:105]
	v_mfma_f32_16x16x32_bf16 v[98:101], v[186:189], v[202:205], v[98:101]
	v_mfma_f32_16x16x32_bf16 v[86:89], v[178:181], v[210:213], v[86:89]
	v_mfma_f32_16x16x32_bf16 v[82:85], v[186:189], v[210:213], v[82:85]
	v_mfma_f32_16x16x32_bf16 v[70:73], v[178:181], v[218:221], v[70:73]
	v_mfma_f32_16x16x32_bf16 v[66:69], v[186:189], v[218:221], v[66:69]
	s_setprio 0
	s_barrier
	s_add_i32 s40, s62, s48
	v_lshl_add_u64 v[152:153], v[152:153], 0, s[20:21]
	s_mov_b32 m0, s40
	ds_read_b128 v[190:193], v158 offset:49152
	ds_read_b128 v[194:197], v158 offset:50176
	ds_read_b128 v[198:201], v158 offset:51200
	ds_read_b128 v[202:205], v158 offset:52224
	ds_read_b128 v[206:209], v158 offset:53248
	ds_read_b128 v[210:213], v158 offset:54272
	ds_read_b128 v[214:217], v158 offset:55296
	ds_read_b128 v[218:221], v158 offset:56320
	global_load_lds_dwordx4 v[152:153], off
	s_add_i32 m0, s40, 0x2000
	s_add_u32 s40, s44, 0x40080
	v_lshl_add_u64 v[152:153], v[172:173], 0, s[20:21]
	s_addc_u32 s41, s45, 0
	s_add_i32 s44, s63, s48
	global_load_lds_dwordx4 v[152:153], off
	v_lshl_add_u64 v[152:153], s[40:41], 0, v[132:133]
	s_mov_b32 m0, s44
	s_nop 0
	global_load_lds_dwordx4 v[152:153], off
	v_lshl_add_u64 v[152:153], s[40:41], 0, v[130:131]
	s_add_i32 m0, s44, 0x2000
	s_nop 0
	global_load_lds_dwordx4 v[152:153], off
	v_lshl_add_u64 v[152:153], v[222:223], 0, s[20:21]
	s_mov_b32 m0, s55
	s_nop 0
	global_load_lds_dwordx4 v[152:153], off
	v_lshl_add_u64 v[152:153], v[224:225], 0, s[20:21]
	s_mov_b32 m0, s56
	s_nop 0
	global_load_lds_dwordx4 v[152:153], off
	s_waitcnt vmcnt(8)
	s_waitcnt lgkmcnt(0)
	s_barrier
	s_setprio 1
	s_waitcnt lgkmcnt(0)
	v_mfma_f32_16x16x32_bf16 v[62:65], v[140:143], v[190:193], v[62:65]
	v_mfma_f32_16x16x32_bf16 v[58:61], v[148:151], v[190:193], v[58:61]
	v_mfma_f32_16x16x32_bf16 v[46:49], v[140:143], v[198:201], v[46:49]
	v_mfma_f32_16x16x32_bf16 v[42:45], v[148:151], v[198:201], v[42:45]
	v_mfma_f32_16x16x32_bf16 v[30:33], v[140:143], v[206:209], v[30:33]
	v_mfma_f32_16x16x32_bf16 v[26:29], v[148:151], v[206:209], v[26:29]
	v_mfma_f32_16x16x32_bf16 v[14:17], v[140:143], v[214:217], v[14:17]
	v_mfma_f32_16x16x32_bf16 v[10:13], v[148:151], v[214:217], v[10:13]
	v_mfma_f32_16x16x32_bf16 v[62:65], v[144:147], v[194:197], v[62:65]
	v_mfma_f32_16x16x32_bf16 v[58:61], v[164:167], v[194:197], v[58:61]
	v_mfma_f32_16x16x32_bf16 v[46:49], v[144:147], v[202:205], v[46:49]
	v_mfma_f32_16x16x32_bf16 v[42:45], v[164:167], v[202:205], v[42:45]
	v_mfma_f32_16x16x32_bf16 v[30:33], v[144:147], v[210:213], v[30:33]
	v_mfma_f32_16x16x32_bf16 v[26:29], v[164:167], v[210:213], v[26:29]
	v_mfma_f32_16x16x32_bf16 v[14:17], v[144:147], v[218:221], v[14:17]
	v_mfma_f32_16x16x32_bf16 v[10:13], v[164:167], v[218:221], v[10:13]
	s_setprio 0
	s_setprio 1
	v_mfma_f32_16x16x32_bf16 v[54:57], v[168:171], v[190:193], v[54:57]
	v_mfma_f32_16x16x32_bf16 v[50:53], v[182:185], v[190:193], v[50:53]
	v_mfma_f32_16x16x32_bf16 v[38:41], v[168:171], v[198:201], v[38:41]
	v_mfma_f32_16x16x32_bf16 v[34:37], v[182:185], v[198:201], v[34:37]
	v_mfma_f32_16x16x32_bf16 v[22:25], v[168:171], v[206:209], v[22:25]
	v_mfma_f32_16x16x32_bf16 v[18:21], v[182:185], v[206:209], v[18:21]
	v_mfma_f32_16x16x32_bf16 v[6:9], v[168:171], v[214:217], v[6:9]
	v_mfma_f32_16x16x32_bf16 v[2:5], v[182:185], v[214:217], v[2:5]
	v_mfma_f32_16x16x32_bf16 v[54:57], v[178:181], v[194:197], v[54:57]
	v_mfma_f32_16x16x32_bf16 v[50:53], v[186:189], v[194:197], v[50:53]
	v_mfma_f32_16x16x32_bf16 v[38:41], v[178:181], v[202:205], v[38:41]
	v_mfma_f32_16x16x32_bf16 v[34:37], v[186:189], v[202:205], v[34:37]
	v_mfma_f32_16x16x32_bf16 v[22:25], v[178:181], v[210:213], v[22:25]
	v_mfma_f32_16x16x32_bf16 v[18:21], v[186:189], v[210:213], v[18:21]
	v_mfma_f32_16x16x32_bf16 v[6:9], v[178:181], v[218:221], v[6:9]
	v_mfma_f32_16x16x32_bf16 v[2:5], v[186:189], v[218:221], v[2:5]
	s_setprio 0
	s_barrier
	s_add_i32 s61, s61, 2
	s_add_u32 s35, s35, 0x100
	s_addc_u32 s39, s39, 0
	s_cmp_gt_u32 s61, 13
	s_mov_b64 s[40:41], s[42:43]
	s_cbranch_scc0 .LBB0_405
	s_branch .Lpeel_exit_405

.Lpeel_exit_405:
	s_and_b64 vcc, exec, s[22:23]
	s_cbranch_vccz .LBB0_408
	s_barrier

.LBB0_1134:
	s_ashr_i32 s29, s28, 31
	s_lshl_b64 s[30:31], s[28:29], 19
	s_add_u32 s30, s3, s30
	s_addc_u32 s31, s14, s31
	s_and_b64 s[34:35], s[0:1], exec
	s_cselect_b32 s29, s31, s39
	s_cselect_b32 s57, s30, s38
	s_ashr_i32 s27, s26, 31
	s_lshl_b64 s[34:35], s[26:27], 19
	s_add_u32 s34, s15, s34
	s_addc_u32 s35, s16, s35
	s_and_b64 s[42:43], s[0:1], exec
	s_cselect_b32 s27, s35, s41
	s_cselect_b32 s58, s34, s40
	s_add_u32 s59, s40, 0x100
	s_addc_u32 s60, s41, 0
	s_mov_b32 s61, -2
	ds_read_b128 v[146:149], v156
	ds_read_b128 v[150:153], v156 offset:1024
	ds_read_b128 v[160:163], v156 offset:2048
	ds_read_b128 v[164:167], v156 offset:3072
	ds_read_b128 v[168:171], v157
	ds_read_b128 v[178:181], v157 offset:1024
	ds_read_b128 v[182:185], v157 offset:2048
	ds_read_b128 v[186:189], v157 offset:3072
	s_add_u32 s40, s38, 0x100
	s_addc_u32 s41, s39, 0
	s_cmp_eq_u32 s61, 12
	s_cselect_b32 s45, s29, s41
	s_cselect_b32 s44, s57, s40
	s_cselect_b32 s43, s27, s60
	s_cselect_b32 s42, s58, s59
	v_lshl_add_u64 v[172:173], s[38:39], 0, v[138:139]
	s_add_i32 m0, s37, 0xc000
	ds_read_b128 v[190:193], v158
	ds_read_b128 v[194:197], v158 offset:1024
	ds_read_b128 v[198:201], v158 offset:2048
	ds_read_b128 v[202:205], v158 offset:3072
	ds_read_b128 v[206:209], v158 offset:4096
	ds_read_b128 v[210:213], v158 offset:5120
	ds_read_b128 v[214:217], v158 offset:6144
	ds_read_b128 v[218:221], v158 offset:7168
	global_load_lds_dwordx4 v[172:173], off
	v_lshl_add_u64 v[172:173], s[38:39], 0, v[140:141]
	s_add_i32 m0, s37, 0xe000
	s_nop 0
	global_load_lds_dwordx4 v[172:173], off
	s_waitcnt vmcnt(8)
	s_waitcnt lgkmcnt(0)
	s_barrier
	s_setprio 1
	s_waitcnt lgkmcnt(0)
	v_mfma_f32_16x16x32_bf16 v[126:129], v[146:149], v[190:193], 0
	v_mfma_f32_16x16x32_bf16 v[122:125], v[160:163], v[190:193], 0
	v_mfma_f32_16x16x32_bf16 v[110:113], v[146:149], v[198:201], 0
	v_mfma_f32_16x16x32_bf16 v[106:109], v[160:163], v[198:201], 0
	v_mfma_f32_16x16x32_bf16 v[94:97], v[146:149], v[206:209], 0
	v_mfma_f32_16x16x32_bf16 v[90:93], v[160:163], v[206:209], 0
	v_mfma_f32_16x16x32_bf16 v[78:81], v[146:149], v[214:217], 0
	v_mfma_f32_16x16x32_bf16 v[74:77], v[160:163], v[214:217], 0
	v_mfma_f32_16x16x32_bf16 v[126:129], v[150:153], v[194:197], v[126:129]
	v_mfma_f32_16x16x32_bf16 v[122:125], v[164:167], v[194:197], v[122:125]
	v_mfma_f32_16x16x32_bf16 v[110:113], v[150:153], v[202:205], v[110:113]
	v_mfma_f32_16x16x32_bf16 v[106:109], v[164:167], v[202:205], v[106:109]
	v_mfma_f32_16x16x32_bf16 v[94:97], v[150:153], v[210:213], v[94:97]
	v_mfma_f32_16x16x32_bf16 v[90:93], v[164:167], v[210:213], v[90:93]
	v_mfma_f32_16x16x32_bf16 v[78:81], v[150:153], v[218:221], v[78:81]
	v_mfma_f32_16x16x32_bf16 v[74:77], v[164:167], v[218:221], v[74:77]
	s_setprio 0
	s_setprio 1
	v_mfma_f32_16x16x32_bf16 v[118:121], v[168:171], v[190:193], 0
	v_mfma_f32_16x16x32_bf16 v[114:117], v[182:185], v[190:193], 0
	v_mfma_f32_16x16x32_bf16 v[102:105], v[168:171], v[198:201], 0
	v_mfma_f32_16x16x32_bf16 v[98:101], v[182:185], v[198:201], 0
	v_mfma_f32_16x16x32_bf16 v[86:89], v[168:171], v[206:209], 0
	v_mfma_f32_16x16x32_bf16 v[82:85], v[182:185], v[206:209], 0
	v_mfma_f32_16x16x32_bf16 v[70:73], v[168:171], v[214:217], 0
	v_mfma_f32_16x16x32_bf16 v[66:69], v[182:185], v[214:217], 0
	v_mfma_f32_16x16x32_bf16 v[118:121], v[178:181], v[194:197], v[118:121]
	v_mfma_f32_16x16x32_bf16 v[114:117], v[186:189], v[194:197], v[114:117]
	v_mfma_f32_16x16x32_bf16 v[102:105], v[178:181], v[202:205], v[102:105]
	v_mfma_f32_16x16x32_bf16 v[98:101], v[186:189], v[202:205], v[98:101]
	v_mfma_f32_16x16x32_bf16 v[86:89], v[178:181], v[210:213], v[86:89]
	v_mfma_f32_16x16x32_bf16 v[82:85], v[186:189], v[210:213], v[82:85]
	v_mfma_f32_16x16x32_bf16 v[70:73], v[178:181], v[218:221], v[70:73]
	v_mfma_f32_16x16x32_bf16 v[66:69], v[186:189], v[218:221], v[66:69]
	s_setprio 0
	s_barrier
	s_add_i32 s38, s54, s46
	v_lshl_add_u64 v[172:173], s[42:43], 0, v[132:133]
	s_mov_b32 m0, s38
	ds_read_b128 v[190:193], v158 offset:16384
	ds_read_b128 v[194:197], v158 offset:17408
	ds_read_b128 v[198:201], v158 offset:18432
	ds_read_b128 v[202:205], v158 offset:19456
	ds_read_b128 v[206:209], v158 offset:20480
	ds_read_b128 v[210:213], v158 offset:21504
	ds_read_b128 v[214:217], v158 offset:22528
	ds_read_b128 v[218:221], v158 offset:23552
	global_load_lds_dwordx4 v[172:173], off
	s_add_i32 m0, s38, 0x2000
	s_add_u32 s38, s42, 0x40000
	v_lshl_add_u64 v[222:223], s[42:43], 0, v[136:137]
	s_addc_u32 s39, s43, 0
	s_add_i32 s62, s55, s46
	global_load_lds_dwordx4 v[222:223], off
	v_lshl_add_u64 v[224:225], s[38:39], 0, v[132:133]
	s_mov_b32 m0, s62
	v_lshl_add_u64 v[226:227], s[44:45], 0, v[134:135]
	global_load_lds_dwordx4 v[224:225], off
	v_lshl_add_u64 v[224:225], s[38:39], 0, v[136:137]
	s_add_i32 m0, s62, 0x2000
	s_nop 0
	global_load_lds_dwordx4 v[224:225], off
	v_lshl_add_u64 v[224:225], s[44:45], 0, v[130:131]
	s_mov_b32 m0, s37
	s_nop 0
	global_load_lds_dwordx4 v[224:225], off
	s_mov_b32 m0, s47
	s_nop 0
	global_load_lds_dwordx4 v[226:227], off
	s_waitcnt vmcnt(8)
	s_waitcnt lgkmcnt(0)
	s_barrier
	s_setprio 1
	s_waitcnt lgkmcnt(0)
	v_mfma_f32_16x16x32_bf16 v[62:65], v[146:149], v[190:193], 0
	v_mfma_f32_16x16x32_bf16 v[58:61], v[160:163], v[190:193], 0
	v_mfma_f32_16x16x32_bf16 v[46:49], v[146:149], v[198:201], 0
	v_mfma_f32_16x16x32_bf16 v[42:45], v[160:163], v[198:201], 0
	v_mfma_f32_16x16x32_bf16 v[30:33], v[146:149], v[206:209], 0
	v_mfma_f32_16x16x32_bf16 v[26:29], v[160:163], v[206:209], 0
	v_mfma_f32_16x16x32_bf16 v[14:17], v[146:149], v[214:217], 0
	v_mfma_f32_16x16x32_bf16 v[10:13], v[160:163], v[214:217], 0
	v_mfma_f32_16x16x32_bf16 v[62:65], v[150:153], v[194:197], v[62:65]
	v_mfma_f32_16x16x32_bf16 v[58:61], v[164:167], v[194:197], v[58:61]
	v_mfma_f32_16x16x32_bf16 v[46:49], v[150:153], v[202:205], v[46:49]
	v_mfma_f32_16x16x32_bf16 v[42:45], v[164:167], v[202:205], v[42:45]
	v_mfma_f32_16x16x32_bf16 v[30:33], v[150:153], v[210:213], v[30:33]
	v_mfma_f32_16x16x32_bf16 v[26:29], v[164:167], v[210:213], v[26:29]
	v_mfma_f32_16x16x32_bf16 v[14:17], v[150:153], v[218:221], v[14:17]
	v_mfma_f32_16x16x32_bf16 v[10:13], v[164:167], v[218:221], v[10:13]
	s_setprio 0
	s_setprio 1
	v_mfma_f32_16x16x32_bf16 v[54:57], v[168:171], v[190:193], 0
	v_mfma_f32_16x16x32_bf16 v[50:53], v[182:185], v[190:193], 0
	v_mfma_f32_16x16x32_bf16 v[38:41], v[168:171], v[198:201], 0
	v_mfma_f32_16x16x32_bf16 v[34:37], v[182:185], v[198:201], 0
	v_mfma_f32_16x16x32_bf16 v[22:25], v[168:171], v[206:209], 0
	v_mfma_f32_16x16x32_bf16 v[18:21], v[182:185], v[206:209], 0
	v_mfma_f32_16x16x32_bf16 v[6:9], v[168:171], v[214:217], 0
	v_mfma_f32_16x16x32_bf16 v[2:5], v[182:185], v[214:217], 0
	v_mfma_f32_16x16x32_bf16 v[54:57], v[178:181], v[194:197], v[54:57]
	v_mfma_f32_16x16x32_bf16 v[50:53], v[186:189], v[194:197], v[50:53]
	v_mfma_f32_16x16x32_bf16 v[38:41], v[178:181], v[202:205], v[38:41]
	v_mfma_f32_16x16x32_bf16 v[34:37], v[186:189], v[202:205], v[34:37]
	v_mfma_f32_16x16x32_bf16 v[22:25], v[178:181], v[210:213], v[22:25]
	v_mfma_f32_16x16x32_bf16 v[18:21], v[186:189], v[210:213], v[18:21]
	v_mfma_f32_16x16x32_bf16 v[6:9], v[178:181], v[218:221], v[6:9]
	v_mfma_f32_16x16x32_bf16 v[2:5], v[186:189], v[218:221], v[2:5]
	s_setprio 0
	s_barrier
	s_add_i32 s62, 0, 0x18000
	v_add_u32_e32 v159, s62, v154
	s_add_i32 s63, 0, 0x1c000
	ds_read_b128 v[146:149], v159
	ds_read_b128 v[150:153], v159 offset:1024
	ds_read_b128 v[160:163], v159 offset:2048
	ds_read_b128 v[164:167], v159 offset:3072
	v_add_u32_e32 v159, s63, v154
	ds_read_b128 v[168:171], v159
	ds_read_b128 v[178:181], v159 offset:1024
	ds_read_b128 v[182:185], v159 offset:2048
	ds_read_b128 v[186:189], v159 offset:3072
	s_add_u32 s38, s44, 0x40000
	s_addc_u32 s39, s45, 0
	s_mov_b32 m0, s48
	v_lshl_add_u64 v[228:229], s[38:39], 0, v[130:131]
	ds_read_b128 v[190:193], v158 offset:32768
	ds_read_b128 v[194:197], v158 offset:33792
	ds_read_b128 v[198:201], v158 offset:34816
	ds_read_b128 v[202:205], v158 offset:35840
	ds_read_b128 v[206:209], v158 offset:36864
	ds_read_b128 v[210:213], v158 offset:37888
	ds_read_b128 v[214:217], v158 offset:38912
	ds_read_b128 v[218:221], v158 offset:39936
	global_load_lds_dwordx4 v[228:229], off
	v_lshl_add_u64 v[228:229], s[38:39], 0, v[134:135]
	s_mov_b32 m0, s49
	s_nop 0
	global_load_lds_dwordx4 v[228:229], off
	s_waitcnt vmcnt(8)
	s_waitcnt lgkmcnt(0)
	s_barrier
	s_setprio 1
	s_waitcnt lgkmcnt(0)
	v_mfma_f32_16x16x32_bf16 v[126:129], v[146:149], v[190:193], v[126:129]
	v_mfma_f32_16x16x32_bf16 v[122:125], v[160:163], v[190:193], v[122:125]
	v_mfma_f32_16x16x32_bf16 v[110:113], v[146:149], v[198:201], v[110:113]
	v_mfma_f32_16x16x32_bf16 v[106:109], v[160:163], v[198:201], v[106:109]
	v_mfma_f32_16x16x32_bf16 v[94:97], v[146:149], v[206:209], v[94:97]
	v_mfma_f32_16x16x32_bf16 v[90:93], v[160:163], v[206:209], v[90:93]
	v_mfma_f32_16x16x32_bf16 v[78:81], v[146:149], v[214:217], v[78:81]
	v_mfma_f32_16x16x32_bf16 v[74:77], v[160:163], v[214:217], v[74:77]
	v_mfma_f32_16x16x32_bf16 v[126:129], v[150:153], v[194:197], v[126:129]
	v_mfma_f32_16x16x32_bf16 v[122:125], v[164:167], v[194:197], v[122:125]
	v_mfma_f32_16x16x32_bf16 v[110:113], v[150:153], v[202:205], v[110:113]
	v_mfma_f32_16x16x32_bf16 v[106:109], v[164:167], v[202:205], v[106:109]
	v_mfma_f32_16x16x32_bf16 v[94:97], v[150:153], v[210:213], v[94:97]
	v_mfma_f32_16x16x32_bf16 v[90:93], v[164:167], v[210:213], v[90:93]
	v_mfma_f32_16x16x32_bf16 v[78:81], v[150:153], v[218:221], v[78:81]
	v_mfma_f32_16x16x32_bf16 v[74:77], v[164:167], v[218:221], v[74:77]
	s_setprio 0
	s_setprio 1
	v_mfma_f32_16x16x32_bf16 v[118:121], v[168:171], v[190:193], v[118:121]
	v_mfma_f32_16x16x32_bf16 v[114:117], v[182:185], v[190:193], v[114:117]
	v_mfma_f32_16x16x32_bf16 v[102:105], v[168:171], v[198:201], v[102:105]
	v_mfma_f32_16x16x32_bf16 v[98:101], v[182:185], v[198:201], v[98:101]
	v_mfma_f32_16x16x32_bf16 v[86:89], v[168:171], v[206:209], v[86:89]
	v_mfma_f32_16x16x32_bf16 v[82:85], v[182:185], v[206:209], v[82:85]
	v_mfma_f32_16x16x32_bf16 v[70:73], v[168:171], v[214:217], v[70:73]
	v_mfma_f32_16x16x32_bf16 v[66:69], v[182:185], v[214:217], v[66:69]
	v_mfma_f32_16x16x32_bf16 v[118:121], v[178:181], v[194:197], v[118:121]
	v_mfma_f32_16x16x32_bf16 v[114:117], v[186:189], v[194:197], v[114:117]
	v_mfma_f32_16x16x32_bf16 v[102:105], v[178:181], v[202:205], v[102:105]
	v_mfma_f32_16x16x32_bf16 v[98:101], v[186:189], v[202:205], v[98:101]
	v_mfma_f32_16x16x32_bf16 v[86:89], v[178:181], v[210:213], v[86:89]
	v_mfma_f32_16x16x32_bf16 v[82:85], v[186:189], v[210:213], v[82:85]
	v_mfma_f32_16x16x32_bf16 v[70:73], v[178:181], v[218:221], v[70:73]
	v_mfma_f32_16x16x32_bf16 v[66:69], v[186:189], v[218:221], v[66:69]
	s_setprio 0
	s_barrier
	s_add_i32 s38, s62, s46
	v_lshl_add_u64 v[172:173], v[172:173], 0, s[12:13]
	s_mov_b32 m0, s38
	ds_read_b128 v[190:193], v158 offset:49152
	ds_read_b128 v[194:197], v158 offset:50176
	ds_read_b128 v[198:201], v158 offset:51200
	ds_read_b128 v[202:205], v158 offset:52224
	ds_read_b128 v[206:209], v158 offset:53248
	ds_read_b128 v[210:213], v158 offset:54272
	ds_read_b128 v[214:217], v158 offset:55296
	ds_read_b128 v[218:221], v158 offset:56320
	global_load_lds_dwordx4 v[172:173], off
	s_add_i32 m0, s38, 0x2000
	s_add_u32 s38, s42, 0x40080
	v_lshl_add_u64 v[172:173], v[222:223], 0, s[12:13]
	s_addc_u32 s39, s43, 0
	s_add_i32 s42, s63, s46
	global_load_lds_dwordx4 v[172:173], off
	v_lshl_add_u64 v[172:173], s[38:39], 0, v[132:133]
	s_mov_b32 m0, s42
	s_nop 0
	global_load_lds_dwordx4 v[172:173], off
	v_lshl_add_u64 v[172:173], s[38:39], 0, v[136:137]
	s_add_i32 m0, s42, 0x2000
	s_nop 0
	global_load_lds_dwordx4 v[172:173], off
	v_lshl_add_u64 v[172:173], v[224:225], 0, s[12:13]
	s_mov_b32 m0, s51
	s_nop 0
	global_load_lds_dwordx4 v[172:173], off
	v_lshl_add_u64 v[172:173], v[226:227], 0, s[12:13]
	s_mov_b32 m0, s52
	s_nop 0
	global_load_lds_dwordx4 v[172:173], off
	s_waitcnt vmcnt(8)
	s_waitcnt lgkmcnt(0)
	s_barrier
	s_setprio 1
	s_waitcnt lgkmcnt(0)
	v_mfma_f32_16x16x32_bf16 v[62:65], v[146:149], v[190:193], v[62:65]
	v_mfma_f32_16x16x32_bf16 v[58:61], v[160:163], v[190:193], v[58:61]
	v_mfma_f32_16x16x32_bf16 v[46:49], v[146:149], v[198:201], v[46:49]
	v_mfma_f32_16x16x32_bf16 v[42:45], v[160:163], v[198:201], v[42:45]
	v_mfma_f32_16x16x32_bf16 v[30:33], v[146:149], v[206:209], v[30:33]
	v_mfma_f32_16x16x32_bf16 v[26:29], v[160:163], v[206:209], v[26:29]
	v_mfma_f32_16x16x32_bf16 v[14:17], v[146:149], v[214:217], v[14:17]
	v_mfma_f32_16x16x32_bf16 v[10:13], v[160:163], v[214:217], v[10:13]
	v_mfma_f32_16x16x32_bf16 v[62:65], v[150:153], v[194:197], v[62:65]
	v_mfma_f32_16x16x32_bf16 v[58:61], v[164:167], v[194:197], v[58:61]
	v_mfma_f32_16x16x32_bf16 v[46:49], v[150:153], v[202:205], v[46:49]
	v_mfma_f32_16x16x32_bf16 v[42:45], v[164:167], v[202:205], v[42:45]
	v_mfma_f32_16x16x32_bf16 v[30:33], v[150:153], v[210:213], v[30:33]
	v_mfma_f32_16x16x32_bf16 v[26:29], v[164:167], v[210:213], v[26:29]
	v_mfma_f32_16x16x32_bf16 v[14:17], v[150:153], v[218:221], v[14:17]
	v_mfma_f32_16x16x32_bf16 v[10:13], v[164:167], v[218:221], v[10:13]
	s_setprio 0
	s_setprio 1
	v_mfma_f32_16x16x32_bf16 v[54:57], v[168:171], v[190:193], v[54:57]
	v_mfma_f32_16x16x32_bf16 v[50:53], v[182:185], v[190:193], v[50:53]
	v_mfma_f32_16x16x32_bf16 v[38:41], v[168:171], v[198:201], v[38:41]
	v_mfma_f32_16x16x32_bf16 v[34:37], v[182:185], v[198:201], v[34:37]
	v_mfma_f32_16x16x32_bf16 v[22:25], v[168:171], v[206:209], v[22:25]
	v_mfma_f32_16x16x32_bf16 v[18:21], v[182:185], v[206:209], v[18:21]
	v_mfma_f32_16x16x32_bf16 v[6:9], v[168:171], v[214:217], v[6:9]
	v_mfma_f32_16x16x32_bf16 v[2:5], v[182:185], v[214:217], v[2:5]
	v_mfma_f32_16x16x32_bf16 v[54:57], v[178:181], v[194:197], v[54:57]
	v_mfma_f32_16x16x32_bf16 v[50:53], v[186:189], v[194:197], v[50:53]
	v_mfma_f32_16x16x32_bf16 v[38:41], v[178:181], v[202:205], v[38:41]
	v_mfma_f32_16x16x32_bf16 v[34:37], v[186:189], v[202:205], v[34:37]
	v_mfma_f32_16x16x32_bf16 v[22:25], v[178:181], v[210:213], v[22:25]
	v_mfma_f32_16x16x32_bf16 v[18:21], v[186:189], v[210:213], v[18:21]
	v_mfma_f32_16x16x32_bf16 v[6:9], v[178:181], v[218:221], v[6:9]
	v_mfma_f32_16x16x32_bf16 v[2:5], v[186:189], v[218:221], v[2:5]
	s_setprio 0
	s_barrier
	s_add_i32 s61, s61, 2
	s_add_u32 s59, s59, 0x100
	s_addc_u32 s60, s60, 0
	s_cmp_gt_u32 s61, 13
	s_mov_b64 s[38:39], s[40:41]
	s_cbranch_scc0 .LBB0_1135
	s_branch .Lpeel_exit_1135

.Lpeel_exit_1135:
	s_and_b64 vcc, exec, s[18:19]
	s_cbranch_vccz .LBB0_1138
	s_barrier

.LBB0_1223:
	s_ashr_i32 s27, s26, 31
	s_lshl_b64 s[28:29], s[26:27], 19
	s_add_u32 s28, s3, s28
	s_addc_u32 s29, s14, s29
	s_and_b64 s[30:31], s[4:5], exec
	s_cselect_b32 s27, s29, s37
	s_cselect_b32 s35, s28, s36
	s_ashr_i32 s25, s24, 31
	s_lshl_b64 s[30:31], s[24:25], 19
	s_add_u32 s30, s15, s30
	s_addc_u32 s31, s16, s31
	s_and_b64 s[40:41], s[4:5], exec
	s_cselect_b32 s25, s31, s39
	s_cselect_b32 s56, s30, s38
	s_add_u32 s57, s38, 0x100
	s_addc_u32 s58, s39, 0
	s_mov_b32 s59, -2
	s_waitcnt lgkmcnt(0)
	ds_read_b128 v[146:149], v154
	ds_read_b128 v[158:161], v154 offset:1024
	ds_read_b128 v[162:165], v154 offset:2048
	ds_read_b128 v[166:169], v154 offset:3072
	ds_read_b128 v[170:173], v155
	ds_read_b128 v[178:181], v155 offset:1024
	ds_read_b128 v[182:185], v155 offset:2048
	ds_read_b128 v[186:189], v155 offset:3072
	s_add_u32 s38, s36, 0x100
	s_addc_u32 s39, s37, 0
	s_cmp_eq_u32 s59, 12
	s_cselect_b32 s43, s27, s39
	s_cselect_b32 s42, s35, s38
	s_cselect_b32 s41, s25, s58
	s_cselect_b32 s40, s56, s57
	v_lshl_add_u64 v[150:151], s[36:37], 0, v[138:139]
	s_add_i32 m0, s44, 0xc000
	ds_read_b128 v[190:193], v156
	ds_read_b128 v[194:197], v156 offset:1024
	ds_read_b128 v[198:201], v156 offset:2048
	ds_read_b128 v[202:205], v156 offset:3072
	ds_read_b128 v[206:209], v156 offset:4096
	ds_read_b128 v[210:213], v156 offset:5120
	ds_read_b128 v[214:217], v156 offset:6144
	ds_read_b128 v[218:221], v156 offset:7168
	global_load_lds_dwordx4 v[150:151], off
	v_lshl_add_u64 v[150:151], s[36:37], 0, v[140:141]
	s_add_i32 m0, s44, 0xe000
	s_nop 0
	global_load_lds_dwordx4 v[150:151], off
	s_waitcnt vmcnt(8)
	s_waitcnt lgkmcnt(0)
	s_barrier
	s_setprio 1
	s_waitcnt lgkmcnt(0)
	v_mfma_f32_16x16x32_bf16 v[126:129], v[146:149], v[190:193], 0
	v_mfma_f32_16x16x32_bf16 v[122:125], v[162:165], v[190:193], 0
	v_mfma_f32_16x16x32_bf16 v[110:113], v[146:149], v[198:201], 0
	v_mfma_f32_16x16x32_bf16 v[106:109], v[162:165], v[198:201], 0
	v_mfma_f32_16x16x32_bf16 v[94:97], v[146:149], v[206:209], 0
	v_mfma_f32_16x16x32_bf16 v[90:93], v[162:165], v[206:209], 0
	v_mfma_f32_16x16x32_bf16 v[78:81], v[146:149], v[214:217], 0
	v_mfma_f32_16x16x32_bf16 v[74:77], v[162:165], v[214:217], 0
	v_mfma_f32_16x16x32_bf16 v[126:129], v[158:161], v[194:197], v[126:129]
	v_mfma_f32_16x16x32_bf16 v[122:125], v[166:169], v[194:197], v[122:125]
	v_mfma_f32_16x16x32_bf16 v[110:113], v[158:161], v[202:205], v[110:113]
	v_mfma_f32_16x16x32_bf16 v[106:109], v[166:169], v[202:205], v[106:109]
	v_mfma_f32_16x16x32_bf16 v[94:97], v[158:161], v[210:213], v[94:97]
	v_mfma_f32_16x16x32_bf16 v[90:93], v[166:169], v[210:213], v[90:93]
	v_mfma_f32_16x16x32_bf16 v[78:81], v[158:161], v[218:221], v[78:81]
	v_mfma_f32_16x16x32_bf16 v[74:77], v[166:169], v[218:221], v[74:77]
	s_setprio 0
	s_setprio 1
	v_mfma_f32_16x16x32_bf16 v[118:121], v[170:173], v[190:193], 0
	v_mfma_f32_16x16x32_bf16 v[114:117], v[182:185], v[190:193], 0
	v_mfma_f32_16x16x32_bf16 v[102:105], v[170:173], v[198:201], 0
	v_mfma_f32_16x16x32_bf16 v[98:101], v[182:185], v[198:201], 0
	v_mfma_f32_16x16x32_bf16 v[86:89], v[170:173], v[206:209], 0
	v_mfma_f32_16x16x32_bf16 v[82:85], v[182:185], v[206:209], 0
	v_mfma_f32_16x16x32_bf16 v[70:73], v[170:173], v[214:217], 0
	v_mfma_f32_16x16x32_bf16 v[66:69], v[182:185], v[214:217], 0
	v_mfma_f32_16x16x32_bf16 v[118:121], v[178:181], v[194:197], v[118:121]
	v_mfma_f32_16x16x32_bf16 v[114:117], v[186:189], v[194:197], v[114:117]
	v_mfma_f32_16x16x32_bf16 v[102:105], v[178:181], v[202:205], v[102:105]
	v_mfma_f32_16x16x32_bf16 v[98:101], v[186:189], v[202:205], v[98:101]
	v_mfma_f32_16x16x32_bf16 v[86:89], v[178:181], v[210:213], v[86:89]
	v_mfma_f32_16x16x32_bf16 v[82:85], v[186:189], v[210:213], v[82:85]
	v_mfma_f32_16x16x32_bf16 v[70:73], v[178:181], v[218:221], v[70:73]
	v_mfma_f32_16x16x32_bf16 v[66:69], v[186:189], v[218:221], v[66:69]
	s_setprio 0
	s_barrier
	s_add_i32 s36, s53, s17
	v_lshl_add_u64 v[150:151], s[40:41], 0, v[132:133]
	s_mov_b32 m0, s36
	ds_read_b128 v[190:193], v156 offset:16384
	ds_read_b128 v[194:197], v156 offset:17408
	ds_read_b128 v[198:201], v156 offset:18432
	ds_read_b128 v[202:205], v156 offset:19456
	ds_read_b128 v[206:209], v156 offset:20480
	ds_read_b128 v[210:213], v156 offset:21504
	ds_read_b128 v[214:217], v156 offset:22528
	ds_read_b128 v[218:221], v156 offset:23552
	global_load_lds_dwordx4 v[150:151], off
	s_add_i32 m0, s36, 0x2000
	s_add_u32 s36, s40, 0x40000
	v_lshl_add_u64 v[222:223], s[40:41], 0, v[136:137]
	s_addc_u32 s37, s41, 0
	s_add_i32 s60, s54, s17
	global_load_lds_dwordx4 v[222:223], off
	v_lshl_add_u64 v[224:225], s[36:37], 0, v[132:133]
	s_mov_b32 m0, s60
	v_lshl_add_u64 v[226:227], s[42:43], 0, v[134:135]
	global_load_lds_dwordx4 v[224:225], off
	v_lshl_add_u64 v[224:225], s[36:37], 0, v[136:137]
	s_add_i32 m0, s60, 0x2000
	s_nop 0
	global_load_lds_dwordx4 v[224:225], off
	v_lshl_add_u64 v[224:225], s[42:43], 0, v[130:131]
	s_mov_b32 m0, s44
	s_nop 0
	global_load_lds_dwordx4 v[224:225], off
	s_mov_b32 m0, s45
	s_nop 0
	global_load_lds_dwordx4 v[226:227], off
	s_waitcnt vmcnt(8)
	s_waitcnt lgkmcnt(0)
	s_barrier
	s_setprio 1
	s_waitcnt lgkmcnt(0)
	v_mfma_f32_16x16x32_bf16 v[62:65], v[146:149], v[190:193], 0
	v_mfma_f32_16x16x32_bf16 v[58:61], v[162:165], v[190:193], 0
	v_mfma_f32_16x16x32_bf16 v[46:49], v[146:149], v[198:201], 0
	v_mfma_f32_16x16x32_bf16 v[42:45], v[162:165], v[198:201], 0
	v_mfma_f32_16x16x32_bf16 v[30:33], v[146:149], v[206:209], 0
	v_mfma_f32_16x16x32_bf16 v[26:29], v[162:165], v[206:209], 0
	v_mfma_f32_16x16x32_bf16 v[14:17], v[146:149], v[214:217], 0
	v_mfma_f32_16x16x32_bf16 v[10:13], v[162:165], v[214:217], 0
	v_mfma_f32_16x16x32_bf16 v[62:65], v[158:161], v[194:197], v[62:65]
	v_mfma_f32_16x16x32_bf16 v[58:61], v[166:169], v[194:197], v[58:61]
	v_mfma_f32_16x16x32_bf16 v[46:49], v[158:161], v[202:205], v[46:49]
	v_mfma_f32_16x16x32_bf16 v[42:45], v[166:169], v[202:205], v[42:45]
	v_mfma_f32_16x16x32_bf16 v[30:33], v[158:161], v[210:213], v[30:33]
	v_mfma_f32_16x16x32_bf16 v[26:29], v[166:169], v[210:213], v[26:29]
	v_mfma_f32_16x16x32_bf16 v[14:17], v[158:161], v[218:221], v[14:17]
	v_mfma_f32_16x16x32_bf16 v[10:13], v[166:169], v[218:221], v[10:13]
	s_setprio 0
	s_setprio 1
	v_mfma_f32_16x16x32_bf16 v[54:57], v[170:173], v[190:193], 0
	v_mfma_f32_16x16x32_bf16 v[50:53], v[182:185], v[190:193], 0
	v_mfma_f32_16x16x32_bf16 v[38:41], v[170:173], v[198:201], 0
	v_mfma_f32_16x16x32_bf16 v[34:37], v[182:185], v[198:201], 0
	v_mfma_f32_16x16x32_bf16 v[22:25], v[170:173], v[206:209], 0
	v_mfma_f32_16x16x32_bf16 v[18:21], v[182:185], v[206:209], 0
	v_mfma_f32_16x16x32_bf16 v[6:9], v[170:173], v[214:217], 0
	v_mfma_f32_16x16x32_bf16 v[2:5], v[182:185], v[214:217], 0
	v_mfma_f32_16x16x32_bf16 v[54:57], v[178:181], v[194:197], v[54:57]
	v_mfma_f32_16x16x32_bf16 v[50:53], v[186:189], v[194:197], v[50:53]
	v_mfma_f32_16x16x32_bf16 v[38:41], v[178:181], v[202:205], v[38:41]
	v_mfma_f32_16x16x32_bf16 v[34:37], v[186:189], v[202:205], v[34:37]
	v_mfma_f32_16x16x32_bf16 v[22:25], v[178:181], v[210:213], v[22:25]
	v_mfma_f32_16x16x32_bf16 v[18:21], v[186:189], v[210:213], v[18:21]
	v_mfma_f32_16x16x32_bf16 v[6:9], v[178:181], v[218:221], v[6:9]
	v_mfma_f32_16x16x32_bf16 v[2:5], v[186:189], v[218:221], v[2:5]
	s_setprio 0
	s_barrier
	s_add_i32 s60, 0, 0x18000
	s_add_i32 s61, 0, 0x1c000
	v_add_u32_e32 v166, s60, v152
	v_add_u32_e32 v177, s61, v152
	ds_read_b128 v[146:149], v166
	ds_read_b128 v[158:161], v166 offset:1024
	ds_read_b128 v[162:165], v166 offset:2048
	ds_read_b128 v[166:169], v166 offset:3072
	ds_read_b128 v[170:173], v177
	ds_read_b128 v[178:181], v177 offset:1024
	ds_read_b128 v[182:185], v177 offset:2048
	ds_read_b128 v[186:189], v177 offset:3072
	s_add_u32 s36, s42, 0x40000
	s_addc_u32 s37, s43, 0
	s_mov_b32 m0, s46
	v_lshl_add_u64 v[228:229], s[36:37], 0, v[130:131]
	ds_read_b128 v[190:193], v156 offset:32768
	ds_read_b128 v[194:197], v156 offset:33792
	ds_read_b128 v[198:201], v156 offset:34816
	ds_read_b128 v[202:205], v156 offset:35840
	ds_read_b128 v[206:209], v156 offset:36864
	ds_read_b128 v[210:213], v156 offset:37888
	ds_read_b128 v[214:217], v156 offset:38912
	ds_read_b128 v[218:221], v156 offset:39936
	global_load_lds_dwordx4 v[228:229], off
	v_lshl_add_u64 v[228:229], s[36:37], 0, v[134:135]
	s_mov_b32 m0, s47
	s_nop 0
	global_load_lds_dwordx4 v[228:229], off
	s_waitcnt vmcnt(8)
	s_waitcnt lgkmcnt(0)
	s_barrier
	s_setprio 1
	s_waitcnt lgkmcnt(0)
	v_mfma_f32_16x16x32_bf16 v[126:129], v[146:149], v[190:193], v[126:129]
	v_mfma_f32_16x16x32_bf16 v[122:125], v[162:165], v[190:193], v[122:125]
	v_mfma_f32_16x16x32_bf16 v[110:113], v[146:149], v[198:201], v[110:113]
	v_mfma_f32_16x16x32_bf16 v[106:109], v[162:165], v[198:201], v[106:109]
	v_mfma_f32_16x16x32_bf16 v[94:97], v[146:149], v[206:209], v[94:97]
	v_mfma_f32_16x16x32_bf16 v[90:93], v[162:165], v[206:209], v[90:93]
	v_mfma_f32_16x16x32_bf16 v[78:81], v[146:149], v[214:217], v[78:81]
	v_mfma_f32_16x16x32_bf16 v[74:77], v[162:165], v[214:217], v[74:77]
	v_mfma_f32_16x16x32_bf16 v[126:129], v[158:161], v[194:197], v[126:129]
	v_mfma_f32_16x16x32_bf16 v[122:125], v[166:169], v[194:197], v[122:125]
	v_mfma_f32_16x16x32_bf16 v[110:113], v[158:161], v[202:205], v[110:113]
	v_mfma_f32_16x16x32_bf16 v[106:109], v[166:169], v[202:205], v[106:109]
	v_mfma_f32_16x16x32_bf16 v[94:97], v[158:161], v[210:213], v[94:97]
	v_mfma_f32_16x16x32_bf16 v[90:93], v[166:169], v[210:213], v[90:93]
	v_mfma_f32_16x16x32_bf16 v[78:81], v[158:161], v[218:221], v[78:81]
	v_mfma_f32_16x16x32_bf16 v[74:77], v[166:169], v[218:221], v[74:77]
	s_setprio 0
	s_setprio 1
	v_mfma_f32_16x16x32_bf16 v[118:121], v[170:173], v[190:193], v[118:121]
	v_mfma_f32_16x16x32_bf16 v[114:117], v[182:185], v[190:193], v[114:117]
	v_mfma_f32_16x16x32_bf16 v[102:105], v[170:173], v[198:201], v[102:105]
	v_mfma_f32_16x16x32_bf16 v[98:101], v[182:185], v[198:201], v[98:101]
	v_mfma_f32_16x16x32_bf16 v[86:89], v[170:173], v[206:209], v[86:89]
	v_mfma_f32_16x16x32_bf16 v[82:85], v[182:185], v[206:209], v[82:85]
	v_mfma_f32_16x16x32_bf16 v[70:73], v[170:173], v[214:217], v[70:73]
	v_mfma_f32_16x16x32_bf16 v[66:69], v[182:185], v[214:217], v[66:69]
	v_mfma_f32_16x16x32_bf16 v[118:121], v[178:181], v[194:197], v[118:121]
	v_mfma_f32_16x16x32_bf16 v[114:117], v[186:189], v[194:197], v[114:117]
	v_mfma_f32_16x16x32_bf16 v[102:105], v[178:181], v[202:205], v[102:105]
	v_mfma_f32_16x16x32_bf16 v[98:101], v[186:189], v[202:205], v[98:101]
	v_mfma_f32_16x16x32_bf16 v[86:89], v[178:181], v[210:213], v[86:89]
	v_mfma_f32_16x16x32_bf16 v[82:85], v[186:189], v[210:213], v[82:85]
	v_mfma_f32_16x16x32_bf16 v[70:73], v[178:181], v[218:221], v[70:73]
	v_mfma_f32_16x16x32_bf16 v[66:69], v[186:189], v[218:221], v[66:69]
	s_setprio 0
	s_barrier
	s_add_i32 s36, s60, s17
	v_lshl_add_u64 v[150:151], v[150:151], 0, s[20:21]
	s_mov_b32 m0, s36
	ds_read_b128 v[190:193], v156 offset:49152
	ds_read_b128 v[194:197], v156 offset:50176
	ds_read_b128 v[198:201], v156 offset:51200
	ds_read_b128 v[202:205], v156 offset:52224
	ds_read_b128 v[206:209], v156 offset:53248
	ds_read_b128 v[210:213], v156 offset:54272
	ds_read_b128 v[214:217], v156 offset:55296
	ds_read_b128 v[218:221], v156 offset:56320
	global_load_lds_dwordx4 v[150:151], off
	s_add_i32 m0, s36, 0x2000
	s_add_u32 s36, s40, 0x40080
	v_lshl_add_u64 v[150:151], v[222:223], 0, s[20:21]
	s_addc_u32 s37, s41, 0
	s_add_i32 s40, s61, s17
	global_load_lds_dwordx4 v[150:151], off
	v_lshl_add_u64 v[150:151], s[36:37], 0, v[132:133]
	s_mov_b32 m0, s40
	s_nop 0
	global_load_lds_dwordx4 v[150:151], off
	v_lshl_add_u64 v[150:151], s[36:37], 0, v[136:137]
	s_add_i32 m0, s40, 0x2000
	s_nop 0
	global_load_lds_dwordx4 v[150:151], off
	v_lshl_add_u64 v[150:151], v[224:225], 0, s[20:21]
	s_mov_b32 m0, s49
	s_nop 0
	global_load_lds_dwordx4 v[150:151], off
	v_lshl_add_u64 v[150:151], v[226:227], 0, s[20:21]
	s_mov_b32 m0, s50
	s_nop 0
	global_load_lds_dwordx4 v[150:151], off
	s_waitcnt vmcnt(8)
	s_waitcnt lgkmcnt(0)
	s_barrier
	s_setprio 1
	s_waitcnt lgkmcnt(0)
	v_mfma_f32_16x16x32_bf16 v[62:65], v[146:149], v[190:193], v[62:65]
	v_mfma_f32_16x16x32_bf16 v[58:61], v[162:165], v[190:193], v[58:61]
	v_mfma_f32_16x16x32_bf16 v[46:49], v[146:149], v[198:201], v[46:49]
	v_mfma_f32_16x16x32_bf16 v[42:45], v[162:165], v[198:201], v[42:45]
	v_mfma_f32_16x16x32_bf16 v[30:33], v[146:149], v[206:209], v[30:33]
	v_mfma_f32_16x16x32_bf16 v[26:29], v[162:165], v[206:209], v[26:29]
	v_mfma_f32_16x16x32_bf16 v[14:17], v[146:149], v[214:217], v[14:17]
	v_mfma_f32_16x16x32_bf16 v[10:13], v[162:165], v[214:217], v[10:13]
	v_mfma_f32_16x16x32_bf16 v[62:65], v[158:161], v[194:197], v[62:65]
	v_mfma_f32_16x16x32_bf16 v[58:61], v[166:169], v[194:197], v[58:61]
	v_mfma_f32_16x16x32_bf16 v[46:49], v[158:161], v[202:205], v[46:49]
	v_mfma_f32_16x16x32_bf16 v[42:45], v[166:169], v[202:205], v[42:45]
	v_mfma_f32_16x16x32_bf16 v[30:33], v[158:161], v[210:213], v[30:33]
	v_mfma_f32_16x16x32_bf16 v[26:29], v[166:169], v[210:213], v[26:29]
	v_mfma_f32_16x16x32_bf16 v[14:17], v[158:161], v[218:221], v[14:17]
	v_mfma_f32_16x16x32_bf16 v[10:13], v[166:169], v[218:221], v[10:13]
	s_setprio 0
	s_setprio 1
	v_mfma_f32_16x16x32_bf16 v[54:57], v[170:173], v[190:193], v[54:57]
	v_mfma_f32_16x16x32_bf16 v[50:53], v[182:185], v[190:193], v[50:53]
	v_mfma_f32_16x16x32_bf16 v[38:41], v[170:173], v[198:201], v[38:41]
	v_mfma_f32_16x16x32_bf16 v[34:37], v[182:185], v[198:201], v[34:37]
	v_mfma_f32_16x16x32_bf16 v[22:25], v[170:173], v[206:209], v[22:25]
	v_mfma_f32_16x16x32_bf16 v[18:21], v[182:185], v[206:209], v[18:21]
	v_mfma_f32_16x16x32_bf16 v[6:9], v[170:173], v[214:217], v[6:9]
	v_mfma_f32_16x16x32_bf16 v[2:5], v[182:185], v[214:217], v[2:5]
	v_mfma_f32_16x16x32_bf16 v[54:57], v[178:181], v[194:197], v[54:57]
	v_mfma_f32_16x16x32_bf16 v[50:53], v[186:189], v[194:197], v[50:53]
	v_mfma_f32_16x16x32_bf16 v[38:41], v[178:181], v[202:205], v[38:41]
	v_mfma_f32_16x16x32_bf16 v[34:37], v[186:189], v[202:205], v[34:37]
	v_mfma_f32_16x16x32_bf16 v[22:25], v[178:181], v[210:213], v[22:25]
	v_mfma_f32_16x16x32_bf16 v[18:21], v[186:189], v[210:213], v[18:21]
	v_mfma_f32_16x16x32_bf16 v[6:9], v[178:181], v[218:221], v[6:9]
	v_mfma_f32_16x16x32_bf16 v[2:5], v[186:189], v[218:221], v[2:5]
	s_setprio 0
	s_barrier
	s_add_i32 s59, s59, 2
	s_add_u32 s57, s57, 0x100
	s_addc_u32 s58, s58, 0
	s_cmp_gt_u32 s59, 13
	s_mov_b64 s[36:37], s[38:39]
	s_cbranch_scc0 .LBB0_1224
	s_branch .Lpeel_exit_1224

.LBB0_1322:
	s_ashr_i32 s23, s22, 31
	s_lshl_b64 s[24:25], s[22:23], 19
	s_add_u32 s24, s3, s24
	s_addc_u32 s25, s14, s25
	s_and_b64 s[26:27], s[0:1], exec
	s_cselect_b32 s23, s25, s29
	s_cselect_b32 s50, s24, s28
	s_ashr_i32 s21, s20, 31
	s_lshl_b64 s[26:27], s[20:21], 19
	s_add_u32 s26, s15, s26
	s_addc_u32 s27, s16, s27
	s_and_b64 s[34:35], s[0:1], exec
	s_cselect_b32 s21, s27, s31
	s_cselect_b32 s51, s26, s30
	s_add_u32 s52, s30, 0x100
	s_addc_u32 s53, s31, 0
	s_mov_b32 s54, -2
	ds_read_b128 v[148:151], v154
	ds_read_b128 v[160:163], v154 offset:1024
	ds_read_b128 v[164:167], v154 offset:2048
	ds_read_b128 v[168:171], v154 offset:3072
	ds_read_b128 v[178:181], v155
	ds_read_b128 v[182:185], v155 offset:1024
	ds_read_b128 v[186:189], v155 offset:2048
	ds_read_b128 v[190:193], v155 offset:3072
	s_add_u32 s30, s28, 0x100
	s_addc_u32 s31, s29, 0
	s_cmp_eq_u32 s54, 12
	s_cselect_b32 s37, s23, s31
	s_cselect_b32 s36, s50, s30
	s_cselect_b32 s35, s21, s53
	s_cselect_b32 s34, s51, s52
	v_lshl_add_u64 v[172:173], s[28:29], 0, v[140:141]
	s_add_i32 m0, s39, 0xc000
	ds_read_b128 v[194:197], v156
	ds_read_b128 v[198:201], v156 offset:1024
	ds_read_b128 v[202:205], v156 offset:2048
	ds_read_b128 v[206:209], v156 offset:3072
	ds_read_b128 v[210:213], v156 offset:4096
	ds_read_b128 v[214:217], v156 offset:5120
	ds_read_b128 v[218:221], v156 offset:6144
	ds_read_b128 v[222:225], v156 offset:7168
	global_load_lds_dwordx4 v[172:173], off
	v_lshl_add_u64 v[172:173], s[28:29], 0, v[142:143]
	s_add_i32 m0, s39, 0xe000
	s_nop 0
	global_load_lds_dwordx4 v[172:173], off
	s_waitcnt vmcnt(8)
	s_waitcnt lgkmcnt(0)
	s_barrier
	s_setprio 1
	s_waitcnt lgkmcnt(0)
	v_mfma_f32_16x16x32_bf16 v[126:129], v[148:151], v[194:197], 0
	v_mfma_f32_16x16x32_bf16 v[122:125], v[164:167], v[194:197], 0
	v_mfma_f32_16x16x32_bf16 v[110:113], v[148:151], v[202:205], 0
	v_mfma_f32_16x16x32_bf16 v[106:109], v[164:167], v[202:205], 0
	v_mfma_f32_16x16x32_bf16 v[94:97], v[148:151], v[210:213], 0
	v_mfma_f32_16x16x32_bf16 v[90:93], v[164:167], v[210:213], 0
	v_mfma_f32_16x16x32_bf16 v[78:81], v[148:151], v[218:221], 0
	v_mfma_f32_16x16x32_bf16 v[74:77], v[164:167], v[218:221], 0
	v_mfma_f32_16x16x32_bf16 v[126:129], v[160:163], v[198:201], v[126:129]
	v_mfma_f32_16x16x32_bf16 v[122:125], v[168:171], v[198:201], v[122:125]
	v_mfma_f32_16x16x32_bf16 v[110:113], v[160:163], v[206:209], v[110:113]
	v_mfma_f32_16x16x32_bf16 v[106:109], v[168:171], v[206:209], v[106:109]
	v_mfma_f32_16x16x32_bf16 v[94:97], v[160:163], v[214:217], v[94:97]
	v_mfma_f32_16x16x32_bf16 v[90:93], v[168:171], v[214:217], v[90:93]
	v_mfma_f32_16x16x32_bf16 v[78:81], v[160:163], v[222:225], v[78:81]
	v_mfma_f32_16x16x32_bf16 v[74:77], v[168:171], v[222:225], v[74:77]
	s_setprio 0
	s_setprio 1
	v_mfma_f32_16x16x32_bf16 v[118:121], v[178:181], v[194:197], 0
	v_mfma_f32_16x16x32_bf16 v[114:117], v[186:189], v[194:197], 0
	v_mfma_f32_16x16x32_bf16 v[102:105], v[178:181], v[202:205], 0
	v_mfma_f32_16x16x32_bf16 v[98:101], v[186:189], v[202:205], 0
	v_mfma_f32_16x16x32_bf16 v[86:89], v[178:181], v[210:213], 0
	v_mfma_f32_16x16x32_bf16 v[82:85], v[186:189], v[210:213], 0
	v_mfma_f32_16x16x32_bf16 v[70:73], v[178:181], v[218:221], 0
	v_mfma_f32_16x16x32_bf16 v[66:69], v[186:189], v[218:221], 0
	v_mfma_f32_16x16x32_bf16 v[118:121], v[182:185], v[198:201], v[118:121]
	v_mfma_f32_16x16x32_bf16 v[114:117], v[190:193], v[198:201], v[114:117]
	v_mfma_f32_16x16x32_bf16 v[102:105], v[182:185], v[206:209], v[102:105]
	v_mfma_f32_16x16x32_bf16 v[98:101], v[190:193], v[206:209], v[98:101]
	v_mfma_f32_16x16x32_bf16 v[86:89], v[182:185], v[214:217], v[86:89]
	v_mfma_f32_16x16x32_bf16 v[82:85], v[190:193], v[214:217], v[82:85]
	v_mfma_f32_16x16x32_bf16 v[70:73], v[182:185], v[222:225], v[70:73]
	v_mfma_f32_16x16x32_bf16 v[66:69], v[190:193], v[222:225], v[66:69]
	s_setprio 0
	s_barrier
	s_add_i32 s28, s47, s38
	v_lshl_add_u64 v[172:173], s[34:35], 0, v[132:133]
	s_mov_b32 m0, s28
	ds_read_b128 v[194:197], v156 offset:16384
	ds_read_b128 v[198:201], v156 offset:17408
	ds_read_b128 v[202:205], v156 offset:18432
	ds_read_b128 v[206:209], v156 offset:19456
	ds_read_b128 v[210:213], v156 offset:20480
	ds_read_b128 v[214:217], v156 offset:21504
	ds_read_b128 v[218:221], v156 offset:22528
	ds_read_b128 v[222:225], v156 offset:23552
	global_load_lds_dwordx4 v[172:173], off
	s_add_i32 m0, s28, 0x2000
	s_add_u32 s28, s34, 0x40000
	v_lshl_add_u64 v[226:227], s[34:35], 0, v[136:137]
	s_addc_u32 s29, s35, 0
	s_add_i32 s55, s48, s38
	global_load_lds_dwordx4 v[226:227], off
	v_lshl_add_u64 v[228:229], s[28:29], 0, v[132:133]
	s_mov_b32 m0, s55
	v_lshl_add_u64 v[230:231], s[36:37], 0, v[134:135]
	global_load_lds_dwordx4 v[228:229], off
	v_lshl_add_u64 v[228:229], s[28:29], 0, v[136:137]
	s_add_i32 m0, s55, 0x2000
	s_nop 0
	global_load_lds_dwordx4 v[228:229], off
	v_lshl_add_u64 v[228:229], s[36:37], 0, v[130:131]
	s_mov_b32 m0, s39
	s_nop 0
	global_load_lds_dwordx4 v[228:229], off
	s_mov_b32 m0, s40
	s_nop 0
	global_load_lds_dwordx4 v[230:231], off
	s_waitcnt vmcnt(8)
	s_waitcnt lgkmcnt(0)
	s_barrier
	s_setprio 1
	s_waitcnt lgkmcnt(0)
	v_mfma_f32_16x16x32_bf16 v[62:65], v[148:151], v[194:197], 0
	v_mfma_f32_16x16x32_bf16 v[58:61], v[164:167], v[194:197], 0
	v_mfma_f32_16x16x32_bf16 v[46:49], v[148:151], v[202:205], 0
	v_mfma_f32_16x16x32_bf16 v[42:45], v[164:167], v[202:205], 0
	v_mfma_f32_16x16x32_bf16 v[30:33], v[148:151], v[210:213], 0
	v_mfma_f32_16x16x32_bf16 v[26:29], v[164:167], v[210:213], 0
	v_mfma_f32_16x16x32_bf16 v[14:17], v[148:151], v[218:221], 0
	v_mfma_f32_16x16x32_bf16 v[10:13], v[164:167], v[218:221], 0
	v_mfma_f32_16x16x32_bf16 v[62:65], v[160:163], v[198:201], v[62:65]
	v_mfma_f32_16x16x32_bf16 v[58:61], v[168:171], v[198:201], v[58:61]
	v_mfma_f32_16x16x32_bf16 v[46:49], v[160:163], v[206:209], v[46:49]
	v_mfma_f32_16x16x32_bf16 v[42:45], v[168:171], v[206:209], v[42:45]
	v_mfma_f32_16x16x32_bf16 v[30:33], v[160:163], v[214:217], v[30:33]
	v_mfma_f32_16x16x32_bf16 v[26:29], v[168:171], v[214:217], v[26:29]
	v_mfma_f32_16x16x32_bf16 v[14:17], v[160:163], v[222:225], v[14:17]
	v_mfma_f32_16x16x32_bf16 v[10:13], v[168:171], v[222:225], v[10:13]
	s_setprio 0
	s_setprio 1
	v_mfma_f32_16x16x32_bf16 v[54:57], v[178:181], v[194:197], 0
	v_mfma_f32_16x16x32_bf16 v[50:53], v[186:189], v[194:197], 0
	v_mfma_f32_16x16x32_bf16 v[38:41], v[178:181], v[202:205], 0
	v_mfma_f32_16x16x32_bf16 v[34:37], v[186:189], v[202:205], 0
	v_mfma_f32_16x16x32_bf16 v[22:25], v[178:181], v[210:213], 0
	v_mfma_f32_16x16x32_bf16 v[18:21], v[186:189], v[210:213], 0
	v_mfma_f32_16x16x32_bf16 v[6:9], v[178:181], v[218:221], 0
	v_mfma_f32_16x16x32_bf16 v[2:5], v[186:189], v[218:221], 0
	v_mfma_f32_16x16x32_bf16 v[54:57], v[182:185], v[198:201], v[54:57]
	v_mfma_f32_16x16x32_bf16 v[50:53], v[190:193], v[198:201], v[50:53]
	v_mfma_f32_16x16x32_bf16 v[38:41], v[182:185], v[206:209], v[38:41]
	v_mfma_f32_16x16x32_bf16 v[34:37], v[190:193], v[206:209], v[34:37]
	v_mfma_f32_16x16x32_bf16 v[22:25], v[182:185], v[214:217], v[22:25]
	v_mfma_f32_16x16x32_bf16 v[18:21], v[190:193], v[214:217], v[18:21]
	v_mfma_f32_16x16x32_bf16 v[6:9], v[182:185], v[222:225], v[6:9]
	v_mfma_f32_16x16x32_bf16 v[2:5], v[190:193], v[222:225], v[2:5]
	s_setprio 0
	s_barrier
	s_add_i32 s55, 0, 0x18000
	v_add_u32_e32 v138, s55, v152
	s_add_i32 s56, 0, 0x1c000
	ds_read_b128 v[148:151], v138
	ds_read_b128 v[160:163], v138 offset:1024
	ds_read_b128 v[164:167], v138 offset:2048
	ds_read_b128 v[168:171], v138 offset:3072
	v_add_u32_e32 v138, s56, v152
	ds_read_b128 v[178:181], v138
	ds_read_b128 v[182:185], v138 offset:1024
	ds_read_b128 v[186:189], v138 offset:2048
	ds_read_b128 v[190:193], v138 offset:3072
	s_add_u32 s28, s36, 0x40000
	s_addc_u32 s29, s37, 0
	s_mov_b32 m0, s41
	v_lshl_add_u64 v[232:233], s[28:29], 0, v[130:131]
	ds_read_b128 v[194:197], v156 offset:32768
	ds_read_b128 v[198:201], v156 offset:33792
	ds_read_b128 v[202:205], v156 offset:34816
	ds_read_b128 v[206:209], v156 offset:35840
	ds_read_b128 v[210:213], v156 offset:36864
	ds_read_b128 v[214:217], v156 offset:37888
	ds_read_b128 v[218:221], v156 offset:38912
	ds_read_b128 v[222:225], v156 offset:39936
	global_load_lds_dwordx4 v[232:233], off
	v_lshl_add_u64 v[232:233], s[28:29], 0, v[134:135]
	s_mov_b32 m0, s42
	s_nop 0
	global_load_lds_dwordx4 v[232:233], off
	s_waitcnt vmcnt(8)
	s_waitcnt lgkmcnt(0)
	s_barrier
	s_setprio 1
	s_waitcnt lgkmcnt(0)
	v_mfma_f32_16x16x32_bf16 v[126:129], v[148:151], v[194:197], v[126:129]
	v_mfma_f32_16x16x32_bf16 v[122:125], v[164:167], v[194:197], v[122:125]
	v_mfma_f32_16x16x32_bf16 v[110:113], v[148:151], v[202:205], v[110:113]
	v_mfma_f32_16x16x32_bf16 v[106:109], v[164:167], v[202:205], v[106:109]
	v_mfma_f32_16x16x32_bf16 v[94:97], v[148:151], v[210:213], v[94:97]
	v_mfma_f32_16x16x32_bf16 v[90:93], v[164:167], v[210:213], v[90:93]
	v_mfma_f32_16x16x32_bf16 v[78:81], v[148:151], v[218:221], v[78:81]
	v_mfma_f32_16x16x32_bf16 v[74:77], v[164:167], v[218:221], v[74:77]
	v_mfma_f32_16x16x32_bf16 v[126:129], v[160:163], v[198:201], v[126:129]
	v_mfma_f32_16x16x32_bf16 v[122:125], v[168:171], v[198:201], v[122:125]
	v_mfma_f32_16x16x32_bf16 v[110:113], v[160:163], v[206:209], v[110:113]
	v_mfma_f32_16x16x32_bf16 v[106:109], v[168:171], v[206:209], v[106:109]
	v_mfma_f32_16x16x32_bf16 v[94:97], v[160:163], v[214:217], v[94:97]
	v_mfma_f32_16x16x32_bf16 v[90:93], v[168:171], v[214:217], v[90:93]
	v_mfma_f32_16x16x32_bf16 v[78:81], v[160:163], v[222:225], v[78:81]
	v_mfma_f32_16x16x32_bf16 v[74:77], v[168:171], v[222:225], v[74:77]
	s_setprio 0
	s_setprio 1
	v_mfma_f32_16x16x32_bf16 v[118:121], v[178:181], v[194:197], v[118:121]
	v_mfma_f32_16x16x32_bf16 v[114:117], v[186:189], v[194:197], v[114:117]
	v_mfma_f32_16x16x32_bf16 v[102:105], v[178:181], v[202:205], v[102:105]
	v_mfma_f32_16x16x32_bf16 v[98:101], v[186:189], v[202:205], v[98:101]
	v_mfma_f32_16x16x32_bf16 v[86:89], v[178:181], v[210:213], v[86:89]
	v_mfma_f32_16x16x32_bf16 v[82:85], v[186:189], v[210:213], v[82:85]
	v_mfma_f32_16x16x32_bf16 v[70:73], v[178:181], v[218:221], v[70:73]
	v_mfma_f32_16x16x32_bf16 v[66:69], v[186:189], v[218:221], v[66:69]
	v_mfma_f32_16x16x32_bf16 v[118:121], v[182:185], v[198:201], v[118:121]
	v_mfma_f32_16x16x32_bf16 v[114:117], v[190:193], v[198:201], v[114:117]
	v_mfma_f32_16x16x32_bf16 v[102:105], v[182:185], v[206:209], v[102:105]
	v_mfma_f32_16x16x32_bf16 v[98:101], v[190:193], v[206:209], v[98:101]
	v_mfma_f32_16x16x32_bf16 v[86:89], v[182:185], v[214:217], v[86:89]
	v_mfma_f32_16x16x32_bf16 v[82:85], v[190:193], v[214:217], v[82:85]
	v_mfma_f32_16x16x32_bf16 v[70:73], v[182:185], v[222:225], v[70:73]
	v_mfma_f32_16x16x32_bf16 v[66:69], v[190:193], v[222:225], v[66:69]
	s_setprio 0
	s_barrier
	s_add_i32 s28, s55, s38
	v_lshl_add_u64 v[172:173], v[172:173], 0, s[12:13]
	s_mov_b32 m0, s28
	ds_read_b128 v[194:197], v156 offset:49152
	ds_read_b128 v[198:201], v156 offset:50176
	ds_read_b128 v[202:205], v156 offset:51200
	ds_read_b128 v[206:209], v156 offset:52224
	ds_read_b128 v[210:213], v156 offset:53248
	ds_read_b128 v[214:217], v156 offset:54272
	ds_read_b128 v[218:221], v156 offset:55296
	ds_read_b128 v[222:225], v156 offset:56320
	global_load_lds_dwordx4 v[172:173], off
	s_add_i32 m0, s28, 0x2000
	s_add_u32 s28, s34, 0x40080
	v_lshl_add_u64 v[172:173], v[226:227], 0, s[12:13]
	s_addc_u32 s29, s35, 0
	s_add_i32 s34, s56, s38
	global_load_lds_dwordx4 v[172:173], off
	v_lshl_add_u64 v[172:173], s[28:29], 0, v[132:133]
	s_mov_b32 m0, s34
	s_nop 0
	global_load_lds_dwordx4 v[172:173], off
	v_lshl_add_u64 v[172:173], s[28:29], 0, v[136:137]
	s_add_i32 m0, s34, 0x2000
	s_nop 0
	global_load_lds_dwordx4 v[172:173], off
	v_lshl_add_u64 v[172:173], v[228:229], 0, s[12:13]
	s_mov_b32 m0, s44
	s_nop 0
	global_load_lds_dwordx4 v[172:173], off
	v_lshl_add_u64 v[172:173], v[230:231], 0, s[12:13]
	s_mov_b32 m0, s45
	s_nop 0
	global_load_lds_dwordx4 v[172:173], off
	s_waitcnt vmcnt(8)
	s_waitcnt lgkmcnt(0)
	s_barrier
	s_setprio 1
	s_waitcnt lgkmcnt(0)
	v_mfma_f32_16x16x32_bf16 v[62:65], v[148:151], v[194:197], v[62:65]
	v_mfma_f32_16x16x32_bf16 v[58:61], v[164:167], v[194:197], v[58:61]
	v_mfma_f32_16x16x32_bf16 v[46:49], v[148:151], v[202:205], v[46:49]
	v_mfma_f32_16x16x32_bf16 v[42:45], v[164:167], v[202:205], v[42:45]
	v_mfma_f32_16x16x32_bf16 v[30:33], v[148:151], v[210:213], v[30:33]
	v_mfma_f32_16x16x32_bf16 v[26:29], v[164:167], v[210:213], v[26:29]
	v_mfma_f32_16x16x32_bf16 v[14:17], v[148:151], v[218:221], v[14:17]
	v_mfma_f32_16x16x32_bf16 v[10:13], v[164:167], v[218:221], v[10:13]
	v_mfma_f32_16x16x32_bf16 v[62:65], v[160:163], v[198:201], v[62:65]
	v_mfma_f32_16x16x32_bf16 v[58:61], v[168:171], v[198:201], v[58:61]
	v_mfma_f32_16x16x32_bf16 v[46:49], v[160:163], v[206:209], v[46:49]
	v_mfma_f32_16x16x32_bf16 v[42:45], v[168:171], v[206:209], v[42:45]
	v_mfma_f32_16x16x32_bf16 v[30:33], v[160:163], v[214:217], v[30:33]
	v_mfma_f32_16x16x32_bf16 v[26:29], v[168:171], v[214:217], v[26:29]
	v_mfma_f32_16x16x32_bf16 v[14:17], v[160:163], v[222:225], v[14:17]
	v_mfma_f32_16x16x32_bf16 v[10:13], v[168:171], v[222:225], v[10:13]
	s_setprio 0
	s_setprio 1
	v_mfma_f32_16x16x32_bf16 v[54:57], v[178:181], v[194:197], v[54:57]
	v_mfma_f32_16x16x32_bf16 v[50:53], v[186:189], v[194:197], v[50:53]
	v_mfma_f32_16x16x32_bf16 v[38:41], v[178:181], v[202:205], v[38:41]
	v_mfma_f32_16x16x32_bf16 v[34:37], v[186:189], v[202:205], v[34:37]
	v_mfma_f32_16x16x32_bf16 v[22:25], v[178:181], v[210:213], v[22:25]
	v_mfma_f32_16x16x32_bf16 v[18:21], v[186:189], v[210:213], v[18:21]
	v_mfma_f32_16x16x32_bf16 v[6:9], v[178:181], v[218:221], v[6:9]
	v_mfma_f32_16x16x32_bf16 v[2:5], v[186:189], v[218:221], v[2:5]
	v_mfma_f32_16x16x32_bf16 v[54:57], v[182:185], v[198:201], v[54:57]
	v_mfma_f32_16x16x32_bf16 v[50:53], v[190:193], v[198:201], v[50:53]
	v_mfma_f32_16x16x32_bf16 v[38:41], v[182:185], v[206:209], v[38:41]
	v_mfma_f32_16x16x32_bf16 v[34:37], v[190:193], v[206:209], v[34:37]
	v_mfma_f32_16x16x32_bf16 v[22:25], v[182:185], v[214:217], v[22:25]
	v_mfma_f32_16x16x32_bf16 v[18:21], v[190:193], v[214:217], v[18:21]
	v_mfma_f32_16x16x32_bf16 v[6:9], v[182:185], v[222:225], v[6:9]
	v_mfma_f32_16x16x32_bf16 v[2:5], v[190:193], v[222:225], v[2:5]
	s_setprio 0
	s_barrier
	s_add_i32 s54, s54, 2
	s_add_u32 s52, s52, 0x100
	s_addc_u32 s53, s53, 0
	s_cmp_gt_u32 s54, 13
	s_mov_b64 s[28:29], s[30:31]
	s_cbranch_scc0 .LBB0_1323
	s_branch .Lpeel_exit_1323

.LBB0_1495:
	s_ashr_i32 s25, s24, 31
	s_lshl_b64 s[26:27], s[24:25], 19
	s_add_u32 s26, s3, s26
	s_addc_u32 s27, s14, s27
	s_and_b64 s[28:29], s[4:5], exec
	s_cselect_b32 s25, s27, s35
	s_cselect_b32 s31, s26, s34
	s_ashr_i32 s23, s22, 31
	s_lshl_b64 s[28:29], s[22:23], 19
	s_add_u32 s28, s15, s28
	s_addc_u32 s29, s16, s29
	s_and_b64 s[38:39], s[4:5], exec
	s_cselect_b32 s23, s29, s37
	s_cselect_b32 s54, s28, s36
	s_add_u32 s55, s36, 0x100
	s_addc_u32 s56, s37, 0
	s_mov_b32 s57, -2
	s_waitcnt lgkmcnt(0)
	ds_read_b128 v[146:149], v153
	ds_read_b128 v[158:161], v153 offset:1024
	ds_read_b128 v[162:165], v153 offset:2048
	ds_read_b128 v[166:169], v153 offset:3072
	ds_read_b128 v[170:173], v154
	ds_read_b128 v[178:181], v154 offset:1024
	ds_read_b128 v[182:185], v154 offset:2048
	ds_read_b128 v[186:189], v154 offset:3072
	s_add_u32 s36, s34, 0x100
	s_addc_u32 s37, s35, 0
	s_cmp_eq_u32 s57, 12
	s_cselect_b32 s41, s25, s37
	s_cselect_b32 s40, s31, s36
	s_cselect_b32 s39, s23, s56
	s_cselect_b32 s38, s54, s55
	v_lshl_add_u64 v[222:223], s[34:35], 0, v[138:139]
	s_add_i32 m0, s42, 0xc000
	ds_read_b128 v[190:193], v155
	ds_read_b128 v[194:197], v155 offset:1024
	ds_read_b128 v[198:201], v155 offset:2048
	ds_read_b128 v[202:205], v155 offset:3072
	ds_read_b128 v[206:209], v155 offset:4096
	ds_read_b128 v[210:213], v155 offset:5120
	ds_read_b128 v[214:217], v155 offset:6144
	ds_read_b128 v[218:221], v155 offset:7168
	global_load_lds_dwordx4 v[222:223], off
	v_lshl_add_u64 v[222:223], s[34:35], 0, v[140:141]
	s_add_i32 m0, s42, 0xe000
	s_nop 0
	global_load_lds_dwordx4 v[222:223], off
	s_waitcnt vmcnt(8)
	s_waitcnt lgkmcnt(0)
	s_barrier
	s_setprio 1
	s_waitcnt lgkmcnt(0)
	v_mfma_f32_16x16x32_bf16 v[126:129], v[146:149], v[190:193], 0
	v_mfma_f32_16x16x32_bf16 v[122:125], v[162:165], v[190:193], 0
	v_mfma_f32_16x16x32_bf16 v[110:113], v[146:149], v[198:201], 0
	v_mfma_f32_16x16x32_bf16 v[106:109], v[162:165], v[198:201], 0
	v_mfma_f32_16x16x32_bf16 v[94:97], v[146:149], v[206:209], 0
	v_mfma_f32_16x16x32_bf16 v[90:93], v[162:165], v[206:209], 0
	v_mfma_f32_16x16x32_bf16 v[78:81], v[146:149], v[214:217], 0
	v_mfma_f32_16x16x32_bf16 v[74:77], v[162:165], v[214:217], 0
	v_mfma_f32_16x16x32_bf16 v[126:129], v[158:161], v[194:197], v[126:129]
	v_mfma_f32_16x16x32_bf16 v[122:125], v[166:169], v[194:197], v[122:125]
	v_mfma_f32_16x16x32_bf16 v[110:113], v[158:161], v[202:205], v[110:113]
	v_mfma_f32_16x16x32_bf16 v[106:109], v[166:169], v[202:205], v[106:109]
	v_mfma_f32_16x16x32_bf16 v[94:97], v[158:161], v[210:213], v[94:97]
	v_mfma_f32_16x16x32_bf16 v[90:93], v[166:169], v[210:213], v[90:93]
	v_mfma_f32_16x16x32_bf16 v[78:81], v[158:161], v[218:221], v[78:81]
	v_mfma_f32_16x16x32_bf16 v[74:77], v[166:169], v[218:221], v[74:77]
	s_setprio 0
	s_setprio 1
	v_mfma_f32_16x16x32_bf16 v[118:121], v[170:173], v[190:193], 0
	v_mfma_f32_16x16x32_bf16 v[114:117], v[182:185], v[190:193], 0
	v_mfma_f32_16x16x32_bf16 v[102:105], v[170:173], v[198:201], 0
	v_mfma_f32_16x16x32_bf16 v[98:101], v[182:185], v[198:201], 0
	v_mfma_f32_16x16x32_bf16 v[86:89], v[170:173], v[206:209], 0
	v_mfma_f32_16x16x32_bf16 v[82:85], v[182:185], v[206:209], 0
	v_mfma_f32_16x16x32_bf16 v[70:73], v[170:173], v[214:217], 0
	v_mfma_f32_16x16x32_bf16 v[66:69], v[182:185], v[214:217], 0
	v_mfma_f32_16x16x32_bf16 v[118:121], v[178:181], v[194:197], v[118:121]
	v_mfma_f32_16x16x32_bf16 v[114:117], v[186:189], v[194:197], v[114:117]
	v_mfma_f32_16x16x32_bf16 v[102:105], v[178:181], v[202:205], v[102:105]
	v_mfma_f32_16x16x32_bf16 v[98:101], v[186:189], v[202:205], v[98:101]
	v_mfma_f32_16x16x32_bf16 v[86:89], v[178:181], v[210:213], v[86:89]
	v_mfma_f32_16x16x32_bf16 v[82:85], v[186:189], v[210:213], v[82:85]
	v_mfma_f32_16x16x32_bf16 v[70:73], v[178:181], v[218:221], v[70:73]
	v_mfma_f32_16x16x32_bf16 v[66:69], v[186:189], v[218:221], v[66:69]
	s_setprio 0
	s_barrier
	s_add_i32 s34, s51, s17
	v_lshl_add_u64 v[222:223], s[38:39], 0, v[132:133]
	s_mov_b32 m0, s34
	ds_read_b128 v[190:193], v155 offset:16384
	ds_read_b128 v[194:197], v155 offset:17408
	ds_read_b128 v[198:201], v155 offset:18432
	ds_read_b128 v[202:205], v155 offset:19456
	ds_read_b128 v[206:209], v155 offset:20480
	ds_read_b128 v[210:213], v155 offset:21504
	ds_read_b128 v[214:217], v155 offset:22528
	ds_read_b128 v[218:221], v155 offset:23552
	global_load_lds_dwordx4 v[222:223], off
	s_add_i32 m0, s34, 0x2000
	s_add_u32 s34, s38, 0x40000
	v_lshl_add_u64 v[224:225], s[38:39], 0, v[136:137]
	s_addc_u32 s35, s39, 0
	s_add_i32 s58, s52, s17
	global_load_lds_dwordx4 v[224:225], off
	v_lshl_add_u64 v[226:227], s[34:35], 0, v[132:133]
	s_mov_b32 m0, s58
	v_lshl_add_u64 v[228:229], s[40:41], 0, v[134:135]
	global_load_lds_dwordx4 v[226:227], off
	v_lshl_add_u64 v[226:227], s[34:35], 0, v[136:137]
	s_add_i32 m0, s58, 0x2000
	s_nop 0
	global_load_lds_dwordx4 v[226:227], off
	v_lshl_add_u64 v[226:227], s[40:41], 0, v[130:131]
	s_mov_b32 m0, s42
	s_nop 0
	global_load_lds_dwordx4 v[226:227], off
	s_mov_b32 m0, s43
	s_nop 0
	global_load_lds_dwordx4 v[228:229], off
	s_waitcnt vmcnt(8)
	s_waitcnt lgkmcnt(0)
	s_barrier
	s_setprio 1
	s_waitcnt lgkmcnt(0)
	v_mfma_f32_16x16x32_bf16 v[62:65], v[146:149], v[190:193], 0
	v_mfma_f32_16x16x32_bf16 v[58:61], v[162:165], v[190:193], 0
	v_mfma_f32_16x16x32_bf16 v[46:49], v[146:149], v[198:201], 0
	v_mfma_f32_16x16x32_bf16 v[42:45], v[162:165], v[198:201], 0
	v_mfma_f32_16x16x32_bf16 v[30:33], v[146:149], v[206:209], 0
	v_mfma_f32_16x16x32_bf16 v[26:29], v[162:165], v[206:209], 0
	v_mfma_f32_16x16x32_bf16 v[14:17], v[146:149], v[214:217], 0
	v_mfma_f32_16x16x32_bf16 v[10:13], v[162:165], v[214:217], 0
	v_mfma_f32_16x16x32_bf16 v[62:65], v[158:161], v[194:197], v[62:65]
	v_mfma_f32_16x16x32_bf16 v[58:61], v[166:169], v[194:197], v[58:61]
	v_mfma_f32_16x16x32_bf16 v[46:49], v[158:161], v[202:205], v[46:49]
	v_mfma_f32_16x16x32_bf16 v[42:45], v[166:169], v[202:205], v[42:45]
	v_mfma_f32_16x16x32_bf16 v[30:33], v[158:161], v[210:213], v[30:33]
	v_mfma_f32_16x16x32_bf16 v[26:29], v[166:169], v[210:213], v[26:29]
	v_mfma_f32_16x16x32_bf16 v[14:17], v[158:161], v[218:221], v[14:17]
	v_mfma_f32_16x16x32_bf16 v[10:13], v[166:169], v[218:221], v[10:13]
	s_setprio 0
	s_setprio 1
	v_mfma_f32_16x16x32_bf16 v[54:57], v[170:173], v[190:193], 0
	v_mfma_f32_16x16x32_bf16 v[50:53], v[182:185], v[190:193], 0
	v_mfma_f32_16x16x32_bf16 v[38:41], v[170:173], v[198:201], 0
	v_mfma_f32_16x16x32_bf16 v[34:37], v[182:185], v[198:201], 0
	v_mfma_f32_16x16x32_bf16 v[22:25], v[170:173], v[206:209], 0
	v_mfma_f32_16x16x32_bf16 v[18:21], v[182:185], v[206:209], 0
	v_mfma_f32_16x16x32_bf16 v[6:9], v[170:173], v[214:217], 0
	v_mfma_f32_16x16x32_bf16 v[2:5], v[182:185], v[214:217], 0
	v_mfma_f32_16x16x32_bf16 v[54:57], v[178:181], v[194:197], v[54:57]
	v_mfma_f32_16x16x32_bf16 v[50:53], v[186:189], v[194:197], v[50:53]
	v_mfma_f32_16x16x32_bf16 v[38:41], v[178:181], v[202:205], v[38:41]
	v_mfma_f32_16x16x32_bf16 v[34:37], v[186:189], v[202:205], v[34:37]
	v_mfma_f32_16x16x32_bf16 v[22:25], v[178:181], v[210:213], v[22:25]
	v_mfma_f32_16x16x32_bf16 v[18:21], v[186:189], v[210:213], v[18:21]
	v_mfma_f32_16x16x32_bf16 v[6:9], v[178:181], v[218:221], v[6:9]
	v_mfma_f32_16x16x32_bf16 v[2:5], v[186:189], v[218:221], v[2:5]
	s_setprio 0
	s_barrier
	s_add_i32 s58, 0, 0x18000
	v_add_u32_e32 v157, s58, v151
	s_add_i32 s59, 0, 0x1c000
	ds_read_b128 v[146:149], v157
	ds_read_b128 v[158:161], v157 offset:1024
	ds_read_b128 v[162:165], v157 offset:2048
	ds_read_b128 v[166:169], v157 offset:3072
	v_add_u32_e32 v157, s59, v151
	ds_read_b128 v[170:173], v157
	ds_read_b128 v[178:181], v157 offset:1024
	ds_read_b128 v[182:185], v157 offset:2048
	ds_read_b128 v[186:189], v157 offset:3072
	s_add_u32 s34, s40, 0x40000
	s_addc_u32 s35, s41, 0
	s_mov_b32 m0, s44
	v_lshl_add_u64 v[230:231], s[34:35], 0, v[130:131]
	ds_read_b128 v[190:193], v155 offset:32768
	ds_read_b128 v[194:197], v155 offset:33792
	ds_read_b128 v[198:201], v155 offset:34816
	ds_read_b128 v[202:205], v155 offset:35840
	ds_read_b128 v[206:209], v155 offset:36864
	ds_read_b128 v[210:213], v155 offset:37888
	ds_read_b128 v[214:217], v155 offset:38912
	ds_read_b128 v[218:221], v155 offset:39936
	global_load_lds_dwordx4 v[230:231], off
	v_lshl_add_u64 v[230:231], s[34:35], 0, v[134:135]
	s_mov_b32 m0, s45
	s_nop 0
	global_load_lds_dwordx4 v[230:231], off
	s_waitcnt vmcnt(8)
	s_waitcnt lgkmcnt(0)
	s_barrier
	s_setprio 1
	s_waitcnt lgkmcnt(0)
	v_mfma_f32_16x16x32_bf16 v[126:129], v[146:149], v[190:193], v[126:129]
	v_mfma_f32_16x16x32_bf16 v[122:125], v[162:165], v[190:193], v[122:125]
	v_mfma_f32_16x16x32_bf16 v[110:113], v[146:149], v[198:201], v[110:113]
	v_mfma_f32_16x16x32_bf16 v[106:109], v[162:165], v[198:201], v[106:109]
	v_mfma_f32_16x16x32_bf16 v[94:97], v[146:149], v[206:209], v[94:97]
	v_mfma_f32_16x16x32_bf16 v[90:93], v[162:165], v[206:209], v[90:93]
	v_mfma_f32_16x16x32_bf16 v[78:81], v[146:149], v[214:217], v[78:81]
	v_mfma_f32_16x16x32_bf16 v[74:77], v[162:165], v[214:217], v[74:77]
	v_mfma_f32_16x16x32_bf16 v[126:129], v[158:161], v[194:197], v[126:129]
	v_mfma_f32_16x16x32_bf16 v[122:125], v[166:169], v[194:197], v[122:125]
	v_mfma_f32_16x16x32_bf16 v[110:113], v[158:161], v[202:205], v[110:113]
	v_mfma_f32_16x16x32_bf16 v[106:109], v[166:169], v[202:205], v[106:109]
	v_mfma_f32_16x16x32_bf16 v[94:97], v[158:161], v[210:213], v[94:97]
	v_mfma_f32_16x16x32_bf16 v[90:93], v[166:169], v[210:213], v[90:93]
	v_mfma_f32_16x16x32_bf16 v[78:81], v[158:161], v[218:221], v[78:81]
	v_mfma_f32_16x16x32_bf16 v[74:77], v[166:169], v[218:221], v[74:77]
	s_setprio 0
	s_setprio 1
	v_mfma_f32_16x16x32_bf16 v[118:121], v[170:173], v[190:193], v[118:121]
	v_mfma_f32_16x16x32_bf16 v[114:117], v[182:185], v[190:193], v[114:117]
	v_mfma_f32_16x16x32_bf16 v[102:105], v[170:173], v[198:201], v[102:105]
	v_mfma_f32_16x16x32_bf16 v[98:101], v[182:185], v[198:201], v[98:101]
	v_mfma_f32_16x16x32_bf16 v[86:89], v[170:173], v[206:209], v[86:89]
	v_mfma_f32_16x16x32_bf16 v[82:85], v[182:185], v[206:209], v[82:85]
	v_mfma_f32_16x16x32_bf16 v[70:73], v[170:173], v[214:217], v[70:73]
	v_mfma_f32_16x16x32_bf16 v[66:69], v[182:185], v[214:217], v[66:69]
	v_mfma_f32_16x16x32_bf16 v[118:121], v[178:181], v[194:197], v[118:121]
	v_mfma_f32_16x16x32_bf16 v[114:117], v[186:189], v[194:197], v[114:117]
	v_mfma_f32_16x16x32_bf16 v[102:105], v[178:181], v[202:205], v[102:105]
	v_mfma_f32_16x16x32_bf16 v[98:101], v[186:189], v[202:205], v[98:101]
	v_mfma_f32_16x16x32_bf16 v[86:89], v[178:181], v[210:213], v[86:89]
	v_mfma_f32_16x16x32_bf16 v[82:85], v[186:189], v[210:213], v[82:85]
	v_mfma_f32_16x16x32_bf16 v[70:73], v[178:181], v[218:221], v[70:73]
	v_mfma_f32_16x16x32_bf16 v[66:69], v[186:189], v[218:221], v[66:69]
	s_setprio 0
	s_barrier
	s_add_i32 s34, s58, s17
	v_lshl_add_u64 v[222:223], v[222:223], 0, s[18:19]
	s_mov_b32 m0, s34
	ds_read_b128 v[190:193], v155 offset:49152
	ds_read_b128 v[194:197], v155 offset:50176
	ds_read_b128 v[198:201], v155 offset:51200
	ds_read_b128 v[202:205], v155 offset:52224
	ds_read_b128 v[206:209], v155 offset:53248
	ds_read_b128 v[210:213], v155 offset:54272
	ds_read_b128 v[214:217], v155 offset:55296
	ds_read_b128 v[218:221], v155 offset:56320
	global_load_lds_dwordx4 v[222:223], off
	s_add_i32 m0, s34, 0x2000
	s_add_u32 s34, s38, 0x40080
	v_lshl_add_u64 v[222:223], v[224:225], 0, s[18:19]
	s_addc_u32 s35, s39, 0
	s_add_i32 s38, s59, s17
	global_load_lds_dwordx4 v[222:223], off
	v_lshl_add_u64 v[222:223], s[34:35], 0, v[132:133]
	s_mov_b32 m0, s38
	s_nop 0
	global_load_lds_dwordx4 v[222:223], off
	v_lshl_add_u64 v[222:223], s[34:35], 0, v[136:137]
	s_add_i32 m0, s38, 0x2000
	s_nop 0
	global_load_lds_dwordx4 v[222:223], off
	v_lshl_add_u64 v[222:223], v[226:227], 0, s[18:19]
	s_mov_b32 m0, s47
	s_nop 0
	global_load_lds_dwordx4 v[222:223], off
	v_lshl_add_u64 v[222:223], v[228:229], 0, s[18:19]
	s_mov_b32 m0, s48
	s_nop 0
	global_load_lds_dwordx4 v[222:223], off
	s_waitcnt vmcnt(8)
	s_waitcnt lgkmcnt(0)
	s_barrier
	s_setprio 1
	s_waitcnt lgkmcnt(0)
	v_mfma_f32_16x16x32_bf16 v[62:65], v[146:149], v[190:193], v[62:65]
	v_mfma_f32_16x16x32_bf16 v[58:61], v[162:165], v[190:193], v[58:61]
	v_mfma_f32_16x16x32_bf16 v[46:49], v[146:149], v[198:201], v[46:49]
	v_mfma_f32_16x16x32_bf16 v[42:45], v[162:165], v[198:201], v[42:45]
	v_mfma_f32_16x16x32_bf16 v[30:33], v[146:149], v[206:209], v[30:33]
	v_mfma_f32_16x16x32_bf16 v[26:29], v[162:165], v[206:209], v[26:29]
	v_mfma_f32_16x16x32_bf16 v[14:17], v[146:149], v[214:217], v[14:17]
	v_mfma_f32_16x16x32_bf16 v[10:13], v[162:165], v[214:217], v[10:13]
	v_mfma_f32_16x16x32_bf16 v[62:65], v[158:161], v[194:197], v[62:65]
	v_mfma_f32_16x16x32_bf16 v[58:61], v[166:169], v[194:197], v[58:61]
	v_mfma_f32_16x16x32_bf16 v[46:49], v[158:161], v[202:205], v[46:49]
	v_mfma_f32_16x16x32_bf16 v[42:45], v[166:169], v[202:205], v[42:45]
	v_mfma_f32_16x16x32_bf16 v[30:33], v[158:161], v[210:213], v[30:33]
	v_mfma_f32_16x16x32_bf16 v[26:29], v[166:169], v[210:213], v[26:29]
	v_mfma_f32_16x16x32_bf16 v[14:17], v[158:161], v[218:221], v[14:17]
	v_mfma_f32_16x16x32_bf16 v[10:13], v[166:169], v[218:221], v[10:13]
	s_setprio 0
	s_setprio 1
	v_mfma_f32_16x16x32_bf16 v[54:57], v[170:173], v[190:193], v[54:57]
	v_mfma_f32_16x16x32_bf16 v[50:53], v[182:185], v[190:193], v[50:53]
	v_mfma_f32_16x16x32_bf16 v[38:41], v[170:173], v[198:201], v[38:41]
	v_mfma_f32_16x16x32_bf16 v[34:37], v[182:185], v[198:201], v[34:37]
	v_mfma_f32_16x16x32_bf16 v[22:25], v[170:173], v[206:209], v[22:25]
	v_mfma_f32_16x16x32_bf16 v[18:21], v[182:185], v[206:209], v[18:21]
	v_mfma_f32_16x16x32_bf16 v[6:9], v[170:173], v[214:217], v[6:9]
	v_mfma_f32_16x16x32_bf16 v[2:5], v[182:185], v[214:217], v[2:5]
	v_mfma_f32_16x16x32_bf16 v[54:57], v[178:181], v[194:197], v[54:57]
	v_mfma_f32_16x16x32_bf16 v[50:53], v[186:189], v[194:197], v[50:53]
	v_mfma_f32_16x16x32_bf16 v[38:41], v[178:181], v[202:205], v[38:41]
	v_mfma_f32_16x16x32_bf16 v[34:37], v[186:189], v[202:205], v[34:37]
	v_mfma_f32_16x16x32_bf16 v[22:25], v[178:181], v[210:213], v[22:25]
	v_mfma_f32_16x16x32_bf16 v[18:21], v[186:189], v[210:213], v[18:21]
	v_mfma_f32_16x16x32_bf16 v[6:9], v[178:181], v[218:221], v[6:9]
	v_mfma_f32_16x16x32_bf16 v[2:5], v[186:189], v[218:221], v[2:5]
	s_setprio 0
	s_barrier
	s_add_i32 s57, s57, 2
	s_add_u32 s55, s55, 0x100
	s_addc_u32 s56, s56, 0
	s_cmp_gt_u32 s57, 13
	s_mov_b64 s[34:35], s[36:37]
	s_cbranch_scc0 .LBB0_1496
	s_branch .Lpeel_exit_1496

.Lpeel_exit_1496:
	s_and_b64 vcc, exec, s[20:21]
	s_cbranch_vccz .LBB0_1499
	s_barrier

.LBB0_1589:
	s_ashr_i32 s21, s20, 31
	s_lshl_b64 s[22:23], s[20:21], 19
	s_add_u32 s22, s14, s22
	s_addc_u32 s23, s15, s23
	s_and_b64 s[24:25], s[0:1], exec
	s_cselect_b32 s21, s23, s27
	s_cselect_b32 s49, s22, s26
	s_ashr_i32 s19, s18, 31
	s_lshl_b64 s[24:25], s[18:19], 19
	s_add_u32 s24, s16, s24
	s_addc_u32 s25, s17, s25
	s_and_b64 s[30:31], s[0:1], exec
	s_cselect_b32 s19, s25, s29
	s_cselect_b32 s50, s24, s28
	s_add_u32 s51, s28, 0x100
	s_addc_u32 s52, s29, 0
	s_mov_b32 s53, -2
	s_waitcnt vmcnt(0)
	ds_read_b128 v[146:149], v155
	ds_read_b128 v[160:163], v155 offset:1024
	ds_read_b128 v[164:167], v155 offset:2048
	ds_read_b128 v[168:171], v155 offset:3072
	ds_read_b128 v[178:181], v156
	ds_read_b128 v[182:185], v156 offset:1024
	ds_read_b128 v[186:189], v156 offset:2048
	ds_read_b128 v[190:193], v156 offset:3072
	s_add_u32 s28, s26, 0x100
	s_addc_u32 s29, s27, 0
	s_cmp_eq_u32 s53, 12
	s_cselect_b32 s35, s21, s29
	s_cselect_b32 s34, s49, s28
	s_cselect_b32 s31, s19, s52
	s_cselect_b32 s30, s50, s51
	v_lshl_add_u64 v[150:151], s[26:27], 0, v[138:139]
	s_add_i32 m0, s37, 0xc000
	ds_read_b128 v[194:197], v157
	ds_read_b128 v[198:201], v157 offset:1024
	ds_read_b128 v[202:205], v157 offset:2048
	ds_read_b128 v[206:209], v157 offset:3072
	ds_read_b128 v[210:213], v157 offset:4096
	ds_read_b128 v[214:217], v157 offset:5120
	ds_read_b128 v[218:221], v157 offset:6144
	ds_read_b128 v[222:225], v157 offset:7168
	global_load_lds_dwordx4 v[150:151], off
	v_lshl_add_u64 v[150:151], s[26:27], 0, v[140:141]
	s_add_i32 m0, s37, 0xe000
	s_nop 0
	global_load_lds_dwordx4 v[150:151], off
	s_waitcnt vmcnt(8)
	s_waitcnt lgkmcnt(0)
	s_barrier
	s_setprio 1
	s_waitcnt lgkmcnt(0)
	v_mfma_f32_16x16x32_bf16 v[126:129], v[146:149], v[194:197], 0
	v_mfma_f32_16x16x32_bf16 v[122:125], v[164:167], v[194:197], 0
	v_mfma_f32_16x16x32_bf16 v[110:113], v[146:149], v[202:205], 0
	v_mfma_f32_16x16x32_bf16 v[106:109], v[164:167], v[202:205], 0
	v_mfma_f32_16x16x32_bf16 v[94:97], v[146:149], v[210:213], 0
	v_mfma_f32_16x16x32_bf16 v[90:93], v[164:167], v[210:213], 0
	v_mfma_f32_16x16x32_bf16 v[78:81], v[146:149], v[218:221], 0
	v_mfma_f32_16x16x32_bf16 v[74:77], v[164:167], v[218:221], 0
	v_mfma_f32_16x16x32_bf16 v[126:129], v[160:163], v[198:201], v[126:129]
	v_mfma_f32_16x16x32_bf16 v[122:125], v[168:171], v[198:201], v[122:125]
	v_mfma_f32_16x16x32_bf16 v[110:113], v[160:163], v[206:209], v[110:113]
	v_mfma_f32_16x16x32_bf16 v[106:109], v[168:171], v[206:209], v[106:109]
	v_mfma_f32_16x16x32_bf16 v[94:97], v[160:163], v[214:217], v[94:97]
	v_mfma_f32_16x16x32_bf16 v[90:93], v[168:171], v[214:217], v[90:93]
	v_mfma_f32_16x16x32_bf16 v[78:81], v[160:163], v[222:225], v[78:81]
	v_mfma_f32_16x16x32_bf16 v[74:77], v[168:171], v[222:225], v[74:77]
	s_setprio 0
	s_setprio 1
	v_mfma_f32_16x16x32_bf16 v[118:121], v[178:181], v[194:197], 0
	v_mfma_f32_16x16x32_bf16 v[114:117], v[186:189], v[194:197], 0
	v_mfma_f32_16x16x32_bf16 v[102:105], v[178:181], v[202:205], 0
	v_mfma_f32_16x16x32_bf16 v[98:101], v[186:189], v[202:205], 0
	v_mfma_f32_16x16x32_bf16 v[86:89], v[178:181], v[210:213], 0
	v_mfma_f32_16x16x32_bf16 v[82:85], v[186:189], v[210:213], 0
	v_mfma_f32_16x16x32_bf16 v[70:73], v[178:181], v[218:221], 0
	v_mfma_f32_16x16x32_bf16 v[66:69], v[186:189], v[218:221], 0
	v_mfma_f32_16x16x32_bf16 v[118:121], v[182:185], v[198:201], v[118:121]
	v_mfma_f32_16x16x32_bf16 v[114:117], v[190:193], v[198:201], v[114:117]
	v_mfma_f32_16x16x32_bf16 v[102:105], v[182:185], v[206:209], v[102:105]
	v_mfma_f32_16x16x32_bf16 v[98:101], v[190:193], v[206:209], v[98:101]
	v_mfma_f32_16x16x32_bf16 v[86:89], v[182:185], v[214:217], v[86:89]
	v_mfma_f32_16x16x32_bf16 v[82:85], v[190:193], v[214:217], v[82:85]
	v_mfma_f32_16x16x32_bf16 v[70:73], v[182:185], v[222:225], v[70:73]
	v_mfma_f32_16x16x32_bf16 v[66:69], v[190:193], v[222:225], v[66:69]
	s_setprio 0
	s_barrier
	s_add_i32 s26, s45, s36
	v_lshl_add_u64 v[150:151], s[30:31], 0, v[132:133]
	s_mov_b32 m0, s26
	ds_read_b128 v[194:197], v157 offset:16384
	ds_read_b128 v[198:201], v157 offset:17408
	ds_read_b128 v[202:205], v157 offset:18432
	ds_read_b128 v[206:209], v157 offset:19456
	ds_read_b128 v[210:213], v157 offset:20480
	ds_read_b128 v[214:217], v157 offset:21504
	ds_read_b128 v[218:221], v157 offset:22528
	ds_read_b128 v[222:225], v157 offset:23552
	global_load_lds_dwordx4 v[150:151], off
	s_add_i32 m0, s26, 0x2000
	s_add_u32 s26, s30, 0x40000
	v_lshl_add_u64 v[172:173], s[30:31], 0, v[136:137]
	s_addc_u32 s27, s31, 0
	s_add_i32 s54, s46, s36
	global_load_lds_dwordx4 v[172:173], off
	v_lshl_add_u64 v[226:227], s[26:27], 0, v[132:133]
	s_mov_b32 m0, s54
	v_lshl_add_u64 v[228:229], s[34:35], 0, v[134:135]
	global_load_lds_dwordx4 v[226:227], off
	v_lshl_add_u64 v[226:227], s[26:27], 0, v[136:137]
	s_add_i32 m0, s54, 0x2000
	s_nop 0
	global_load_lds_dwordx4 v[226:227], off
	v_lshl_add_u64 v[226:227], s[34:35], 0, v[130:131]
	s_mov_b32 m0, s37
	s_nop 0
	global_load_lds_dwordx4 v[226:227], off
	s_mov_b32 m0, s38
	s_nop 0
	global_load_lds_dwordx4 v[228:229], off
	s_waitcnt vmcnt(8)
	s_waitcnt lgkmcnt(0)
	s_barrier
	s_setprio 1
	s_waitcnt lgkmcnt(0)
	v_mfma_f32_16x16x32_bf16 v[62:65], v[146:149], v[194:197], 0
	v_mfma_f32_16x16x32_bf16 v[58:61], v[164:167], v[194:197], 0
	v_mfma_f32_16x16x32_bf16 v[46:49], v[146:149], v[202:205], 0
	v_mfma_f32_16x16x32_bf16 v[42:45], v[164:167], v[202:205], 0
	v_mfma_f32_16x16x32_bf16 v[30:33], v[146:149], v[210:213], 0
	v_mfma_f32_16x16x32_bf16 v[26:29], v[164:167], v[210:213], 0
	v_mfma_f32_16x16x32_bf16 v[14:17], v[146:149], v[218:221], 0
	v_mfma_f32_16x16x32_bf16 v[10:13], v[164:167], v[218:221], 0
	v_mfma_f32_16x16x32_bf16 v[62:65], v[160:163], v[198:201], v[62:65]
	v_mfma_f32_16x16x32_bf16 v[58:61], v[168:171], v[198:201], v[58:61]
	v_mfma_f32_16x16x32_bf16 v[46:49], v[160:163], v[206:209], v[46:49]
	v_mfma_f32_16x16x32_bf16 v[42:45], v[168:171], v[206:209], v[42:45]
	v_mfma_f32_16x16x32_bf16 v[30:33], v[160:163], v[214:217], v[30:33]
	v_mfma_f32_16x16x32_bf16 v[26:29], v[168:171], v[214:217], v[26:29]
	v_mfma_f32_16x16x32_bf16 v[14:17], v[160:163], v[222:225], v[14:17]
	v_mfma_f32_16x16x32_bf16 v[10:13], v[168:171], v[222:225], v[10:13]
	s_setprio 0
	s_setprio 1
	v_mfma_f32_16x16x32_bf16 v[54:57], v[178:181], v[194:197], 0
	v_mfma_f32_16x16x32_bf16 v[50:53], v[186:189], v[194:197], 0
	v_mfma_f32_16x16x32_bf16 v[38:41], v[178:181], v[202:205], 0
	v_mfma_f32_16x16x32_bf16 v[34:37], v[186:189], v[202:205], 0
	v_mfma_f32_16x16x32_bf16 v[22:25], v[178:181], v[210:213], 0
	v_mfma_f32_16x16x32_bf16 v[18:21], v[186:189], v[210:213], 0
	v_mfma_f32_16x16x32_bf16 v[6:9], v[178:181], v[218:221], 0
	v_mfma_f32_16x16x32_bf16 v[2:5], v[186:189], v[218:221], 0
	v_mfma_f32_16x16x32_bf16 v[54:57], v[182:185], v[198:201], v[54:57]
	v_mfma_f32_16x16x32_bf16 v[50:53], v[190:193], v[198:201], v[50:53]
	v_mfma_f32_16x16x32_bf16 v[38:41], v[182:185], v[206:209], v[38:41]
	v_mfma_f32_16x16x32_bf16 v[34:37], v[190:193], v[206:209], v[34:37]
	v_mfma_f32_16x16x32_bf16 v[22:25], v[182:185], v[214:217], v[22:25]
	v_mfma_f32_16x16x32_bf16 v[18:21], v[190:193], v[214:217], v[18:21]
	v_mfma_f32_16x16x32_bf16 v[6:9], v[182:185], v[222:225], v[6:9]
	v_mfma_f32_16x16x32_bf16 v[2:5], v[190:193], v[222:225], v[2:5]
	s_setprio 0
	s_barrier
	s_add_i32 s54, 0, 0x18000
	s_add_i32 s55, 0, 0x1c000
	v_add_u32_e32 v168, s54, v153
	v_add_u32_e32 v177, s55, v153
	ds_read_b128 v[146:149], v168
	ds_read_b128 v[160:163], v168 offset:1024
	ds_read_b128 v[164:167], v168 offset:2048
	ds_read_b128 v[168:171], v168 offset:3072
	ds_read_b128 v[178:181], v177
	ds_read_b128 v[182:185], v177 offset:1024
	ds_read_b128 v[186:189], v177 offset:2048
	ds_read_b128 v[190:193], v177 offset:3072
	s_add_u32 s26, s34, 0x40000
	s_addc_u32 s27, s35, 0
	s_mov_b32 m0, s39
	v_lshl_add_u64 v[230:231], s[26:27], 0, v[130:131]
	ds_read_b128 v[194:197], v157 offset:32768
	ds_read_b128 v[198:201], v157 offset:33792
	ds_read_b128 v[202:205], v157 offset:34816
	ds_read_b128 v[206:209], v157 offset:35840
	ds_read_b128 v[210:213], v157 offset:36864
	ds_read_b128 v[214:217], v157 offset:37888
	ds_read_b128 v[218:221], v157 offset:38912
	ds_read_b128 v[222:225], v157 offset:39936
	global_load_lds_dwordx4 v[230:231], off
	v_lshl_add_u64 v[230:231], s[26:27], 0, v[134:135]
	s_mov_b32 m0, s40
	s_nop 0
	global_load_lds_dwordx4 v[230:231], off
	s_waitcnt vmcnt(8)
	s_waitcnt lgkmcnt(0)
	s_barrier
	s_setprio 1
	s_waitcnt lgkmcnt(0)
	v_mfma_f32_16x16x32_bf16 v[126:129], v[146:149], v[194:197], v[126:129]
	v_mfma_f32_16x16x32_bf16 v[122:125], v[164:167], v[194:197], v[122:125]
	v_mfma_f32_16x16x32_bf16 v[110:113], v[146:149], v[202:205], v[110:113]
	v_mfma_f32_16x16x32_bf16 v[106:109], v[164:167], v[202:205], v[106:109]
	v_mfma_f32_16x16x32_bf16 v[94:97], v[146:149], v[210:213], v[94:97]
	v_mfma_f32_16x16x32_bf16 v[90:93], v[164:167], v[210:213], v[90:93]
	v_mfma_f32_16x16x32_bf16 v[78:81], v[146:149], v[218:221], v[78:81]
	v_mfma_f32_16x16x32_bf16 v[74:77], v[164:167], v[218:221], v[74:77]
	v_mfma_f32_16x16x32_bf16 v[126:129], v[160:163], v[198:201], v[126:129]
	v_mfma_f32_16x16x32_bf16 v[122:125], v[168:171], v[198:201], v[122:125]
	v_mfma_f32_16x16x32_bf16 v[110:113], v[160:163], v[206:209], v[110:113]
	v_mfma_f32_16x16x32_bf16 v[106:109], v[168:171], v[206:209], v[106:109]
	v_mfma_f32_16x16x32_bf16 v[94:97], v[160:163], v[214:217], v[94:97]
	v_mfma_f32_16x16x32_bf16 v[90:93], v[168:171], v[214:217], v[90:93]
	v_mfma_f32_16x16x32_bf16 v[78:81], v[160:163], v[222:225], v[78:81]
	v_mfma_f32_16x16x32_bf16 v[74:77], v[168:171], v[222:225], v[74:77]
	s_setprio 0
	s_setprio 1
	v_mfma_f32_16x16x32_bf16 v[118:121], v[178:181], v[194:197], v[118:121]
	v_mfma_f32_16x16x32_bf16 v[114:117], v[186:189], v[194:197], v[114:117]
	v_mfma_f32_16x16x32_bf16 v[102:105], v[178:181], v[202:205], v[102:105]
	v_mfma_f32_16x16x32_bf16 v[98:101], v[186:189], v[202:205], v[98:101]
	v_mfma_f32_16x16x32_bf16 v[86:89], v[178:181], v[210:213], v[86:89]
	v_mfma_f32_16x16x32_bf16 v[82:85], v[186:189], v[210:213], v[82:85]
	v_mfma_f32_16x16x32_bf16 v[70:73], v[178:181], v[218:221], v[70:73]
	v_mfma_f32_16x16x32_bf16 v[66:69], v[186:189], v[218:221], v[66:69]
	v_mfma_f32_16x16x32_bf16 v[118:121], v[182:185], v[198:201], v[118:121]
	v_mfma_f32_16x16x32_bf16 v[114:117], v[190:193], v[198:201], v[114:117]
	v_mfma_f32_16x16x32_bf16 v[102:105], v[182:185], v[206:209], v[102:105]
	v_mfma_f32_16x16x32_bf16 v[98:101], v[190:193], v[206:209], v[98:101]
	v_mfma_f32_16x16x32_bf16 v[86:89], v[182:185], v[214:217], v[86:89]
	v_mfma_f32_16x16x32_bf16 v[82:85], v[190:193], v[214:217], v[82:85]
	v_mfma_f32_16x16x32_bf16 v[70:73], v[182:185], v[222:225], v[70:73]
	v_mfma_f32_16x16x32_bf16 v[66:69], v[190:193], v[222:225], v[66:69]
	s_setprio 0
	s_barrier
	s_add_i32 s26, s54, s36
	v_lshl_add_u64 v[150:151], v[150:151], 0, s[10:11]
	s_mov_b32 m0, s26
	ds_read_b128 v[194:197], v157 offset:49152
	ds_read_b128 v[198:201], v157 offset:50176
	ds_read_b128 v[202:205], v157 offset:51200
	ds_read_b128 v[206:209], v157 offset:52224
	ds_read_b128 v[210:213], v157 offset:53248
	ds_read_b128 v[214:217], v157 offset:54272
	ds_read_b128 v[218:221], v157 offset:55296
	ds_read_b128 v[222:225], v157 offset:56320
	global_load_lds_dwordx4 v[150:151], off
	s_add_i32 m0, s26, 0x2000
	s_add_u32 s26, s30, 0x40080
	v_lshl_add_u64 v[150:151], v[172:173], 0, s[10:11]
	s_addc_u32 s27, s31, 0
	s_add_i32 s30, s55, s36
	global_load_lds_dwordx4 v[150:151], off
	v_lshl_add_u64 v[150:151], s[26:27], 0, v[132:133]
	s_mov_b32 m0, s30
	s_nop 0
	global_load_lds_dwordx4 v[150:151], off
	v_lshl_add_u64 v[150:151], s[26:27], 0, v[136:137]
	s_add_i32 m0, s30, 0x2000
	s_nop 0
	global_load_lds_dwordx4 v[150:151], off
	v_lshl_add_u64 v[150:151], v[226:227], 0, s[10:11]
	s_mov_b32 m0, s42
	s_nop 0
	global_load_lds_dwordx4 v[150:151], off
	v_lshl_add_u64 v[150:151], v[228:229], 0, s[10:11]
	s_mov_b32 m0, s43
	s_nop 0
	global_load_lds_dwordx4 v[150:151], off
	s_waitcnt vmcnt(8)
	s_waitcnt lgkmcnt(0)
	s_barrier
	s_setprio 1
	s_waitcnt lgkmcnt(0)
	v_mfma_f32_16x16x32_bf16 v[62:65], v[146:149], v[194:197], v[62:65]
	v_mfma_f32_16x16x32_bf16 v[58:61], v[164:167], v[194:197], v[58:61]
	v_mfma_f32_16x16x32_bf16 v[46:49], v[146:149], v[202:205], v[46:49]
	v_mfma_f32_16x16x32_bf16 v[42:45], v[164:167], v[202:205], v[42:45]
	v_mfma_f32_16x16x32_bf16 v[30:33], v[146:149], v[210:213], v[30:33]
	v_mfma_f32_16x16x32_bf16 v[26:29], v[164:167], v[210:213], v[26:29]
	v_mfma_f32_16x16x32_bf16 v[14:17], v[146:149], v[218:221], v[14:17]
	v_mfma_f32_16x16x32_bf16 v[10:13], v[164:167], v[218:221], v[10:13]
	v_mfma_f32_16x16x32_bf16 v[62:65], v[160:163], v[198:201], v[62:65]
	v_mfma_f32_16x16x32_bf16 v[58:61], v[168:171], v[198:201], v[58:61]
	v_mfma_f32_16x16x32_bf16 v[46:49], v[160:163], v[206:209], v[46:49]
	v_mfma_f32_16x16x32_bf16 v[42:45], v[168:171], v[206:209], v[42:45]
	v_mfma_f32_16x16x32_bf16 v[30:33], v[160:163], v[214:217], v[30:33]
	v_mfma_f32_16x16x32_bf16 v[26:29], v[168:171], v[214:217], v[26:29]
	v_mfma_f32_16x16x32_bf16 v[14:17], v[160:163], v[222:225], v[14:17]
	v_mfma_f32_16x16x32_bf16 v[10:13], v[168:171], v[222:225], v[10:13]
	s_setprio 0
	s_setprio 1
	v_mfma_f32_16x16x32_bf16 v[54:57], v[178:181], v[194:197], v[54:57]
	v_mfma_f32_16x16x32_bf16 v[50:53], v[186:189], v[194:197], v[50:53]
	v_mfma_f32_16x16x32_bf16 v[38:41], v[178:181], v[202:205], v[38:41]
	v_mfma_f32_16x16x32_bf16 v[34:37], v[186:189], v[202:205], v[34:37]
	v_mfma_f32_16x16x32_bf16 v[22:25], v[178:181], v[210:213], v[22:25]
	v_mfma_f32_16x16x32_bf16 v[18:21], v[186:189], v[210:213], v[18:21]
	v_mfma_f32_16x16x32_bf16 v[6:9], v[178:181], v[218:221], v[6:9]
	v_mfma_f32_16x16x32_bf16 v[2:5], v[186:189], v[218:221], v[2:5]
	v_mfma_f32_16x16x32_bf16 v[54:57], v[182:185], v[198:201], v[54:57]
	v_mfma_f32_16x16x32_bf16 v[50:53], v[190:193], v[198:201], v[50:53]
	v_mfma_f32_16x16x32_bf16 v[38:41], v[182:185], v[206:209], v[38:41]
	v_mfma_f32_16x16x32_bf16 v[34:37], v[190:193], v[206:209], v[34:37]
	v_mfma_f32_16x16x32_bf16 v[22:25], v[182:185], v[214:217], v[22:25]
	v_mfma_f32_16x16x32_bf16 v[18:21], v[190:193], v[214:217], v[18:21]
	v_mfma_f32_16x16x32_bf16 v[6:9], v[182:185], v[222:225], v[6:9]
	v_mfma_f32_16x16x32_bf16 v[2:5], v[190:193], v[222:225], v[2:5]
	s_setprio 0
	s_barrier
	s_add_i32 s53, s53, 2
	s_add_u32 s51, s51, 0x100
	s_addc_u32 s52, s52, 0
	s_cmp_gt_u32 s53, 13
	s_mov_b64 s[26:27], s[28:29]
	s_cbranch_scc0 .LBB0_1590
	s_branch .Lpeel_exit_1590

.Lpeel_exit_1590:
	s_and_b64 vcc, exec, s[12:13]
	s_cbranch_vccz .LBB0_1593
	s_barrier

.LBB0_1683:
	s_add_u32 s49, s28, 0x100
	s_addc_u32 s50, s29, 0
	s_mov_b32 s51, -2
	s_waitcnt lgkmcnt(0)
	ds_read_b128 v[144:147], v151
	ds_read_b128 v[156:159], v151 offset:1024
	ds_read_b128 v[160:163], v151 offset:2048
	ds_read_b128 v[164:167], v151 offset:3072
	ds_read_b128 v[168:171], v152
	ds_read_b128 v[176:179], v152 offset:1024
	ds_read_b128 v[180:183], v152 offset:2048
	ds_read_b128 v[184:187], v152 offset:3072
	s_add_u32 s28, s26, 0x100
	s_addc_u32 s29, s27, 0
	s_cmp_eq_u32 s51, 40
	s_cselect_b32 s35, s7, s29
	s_cselect_b32 s34, s6, s28
	s_cselect_b32 s31, s25, s50
	s_cselect_b32 s30, s24, s49
	v_lshl_add_u64 v[172:173], s[26:27], 0, v[136:137]
	s_add_i32 m0, s16, 0xc000
	ds_read_b128 v[188:191], v153
	ds_read_b128 v[192:195], v153 offset:1024
	ds_read_b128 v[196:199], v153 offset:2048
	ds_read_b128 v[200:203], v153 offset:3072
	ds_read_b128 v[204:207], v153 offset:4096
	ds_read_b128 v[208:211], v153 offset:5120
	ds_read_b128 v[212:215], v153 offset:6144
	ds_read_b128 v[216:219], v153 offset:7168
	global_load_lds_dwordx4 v[172:173], off
	v_lshl_add_u64 v[172:173], s[26:27], 0, v[138:139]
	s_add_i32 m0, s16, 0xe000
	s_nop 0
	global_load_lds_dwordx4 v[172:173], off
	s_waitcnt vmcnt(8)
	s_waitcnt lgkmcnt(0)
	s_barrier
	s_setprio 1
	s_waitcnt lgkmcnt(0)
	v_mfma_f32_16x16x32_bf16 v[124:127], v[144:147], v[188:191], 0
	v_mfma_f32_16x16x32_bf16 v[120:123], v[160:163], v[188:191], 0
	v_mfma_f32_16x16x32_bf16 v[108:111], v[144:147], v[196:199], 0
	v_mfma_f32_16x16x32_bf16 v[104:107], v[160:163], v[196:199], 0
	v_mfma_f32_16x16x32_bf16 v[92:95], v[144:147], v[204:207], 0
	v_mfma_f32_16x16x32_bf16 v[88:91], v[160:163], v[204:207], 0
	v_mfma_f32_16x16x32_bf16 v[76:79], v[144:147], v[212:215], 0
	v_mfma_f32_16x16x32_bf16 v[72:75], v[160:163], v[212:215], 0
	v_mfma_f32_16x16x32_bf16 v[124:127], v[156:159], v[192:195], v[124:127]
	v_mfma_f32_16x16x32_bf16 v[120:123], v[164:167], v[192:195], v[120:123]
	v_mfma_f32_16x16x32_bf16 v[108:111], v[156:159], v[200:203], v[108:111]
	v_mfma_f32_16x16x32_bf16 v[104:107], v[164:167], v[200:203], v[104:107]
	v_mfma_f32_16x16x32_bf16 v[92:95], v[156:159], v[208:211], v[92:95]
	v_mfma_f32_16x16x32_bf16 v[88:91], v[164:167], v[208:211], v[88:91]
	v_mfma_f32_16x16x32_bf16 v[76:79], v[156:159], v[216:219], v[76:79]
	v_mfma_f32_16x16x32_bf16 v[72:75], v[164:167], v[216:219], v[72:75]
	s_setprio 0
	s_setprio 1
	v_mfma_f32_16x16x32_bf16 v[116:119], v[168:171], v[188:191], 0
	v_mfma_f32_16x16x32_bf16 v[112:115], v[180:183], v[188:191], 0
	v_mfma_f32_16x16x32_bf16 v[100:103], v[168:171], v[196:199], 0
	v_mfma_f32_16x16x32_bf16 v[96:99], v[180:183], v[196:199], 0
	v_mfma_f32_16x16x32_bf16 v[84:87], v[168:171], v[204:207], 0
	v_mfma_f32_16x16x32_bf16 v[80:83], v[180:183], v[204:207], 0
	v_mfma_f32_16x16x32_bf16 v[68:71], v[168:171], v[212:215], 0
	v_mfma_f32_16x16x32_bf16 v[64:67], v[180:183], v[212:215], 0
	v_mfma_f32_16x16x32_bf16 v[116:119], v[176:179], v[192:195], v[116:119]
	v_mfma_f32_16x16x32_bf16 v[112:115], v[184:187], v[192:195], v[112:115]
	v_mfma_f32_16x16x32_bf16 v[100:103], v[176:179], v[200:203], v[100:103]
	v_mfma_f32_16x16x32_bf16 v[96:99], v[184:187], v[200:203], v[96:99]
	v_mfma_f32_16x16x32_bf16 v[84:87], v[176:179], v[208:211], v[84:87]
	v_mfma_f32_16x16x32_bf16 v[80:83], v[184:187], v[208:211], v[80:83]
	v_mfma_f32_16x16x32_bf16 v[68:71], v[176:179], v[216:219], v[68:71]
	v_mfma_f32_16x16x32_bf16 v[64:67], v[184:187], v[216:219], v[64:67]
	s_setprio 0
	s_barrier
	s_add_i32 s26, s43, s15
	v_lshl_add_u64 v[172:173], s[30:31], 0, v[130:131]
	s_mov_b32 m0, s26
	ds_read_b128 v[188:191], v153 offset:16384
	ds_read_b128 v[192:195], v153 offset:17408
	ds_read_b128 v[196:199], v153 offset:18432
	ds_read_b128 v[200:203], v153 offset:19456
	ds_read_b128 v[204:207], v153 offset:20480
	ds_read_b128 v[208:211], v153 offset:21504
	ds_read_b128 v[212:215], v153 offset:22528
	ds_read_b128 v[216:219], v153 offset:23552
	global_load_lds_dwordx4 v[172:173], off
	s_add_i32 m0, s26, 0x2000
	s_add_u32 s26, s30, 0xb0000
	v_lshl_add_u64 v[220:221], s[30:31], 0, v[134:135]
	s_addc_u32 s27, s31, 0
	s_add_i32 s52, s44, s15
	global_load_lds_dwordx4 v[220:221], off
	v_lshl_add_u64 v[222:223], s[26:27], 0, v[130:131]
	s_mov_b32 m0, s52
	v_lshl_add_u64 v[224:225], s[34:35], 0, v[132:133]
	global_load_lds_dwordx4 v[222:223], off
	v_lshl_add_u64 v[222:223], s[26:27], 0, v[134:135]
	s_add_i32 m0, s52, 0x2000
	s_nop 0
	global_load_lds_dwordx4 v[222:223], off
	v_lshl_add_u64 v[222:223], s[34:35], 0, v[128:129]
	s_mov_b32 m0, s16
	s_nop 0
	global_load_lds_dwordx4 v[222:223], off
	s_mov_b32 m0, s17
	s_nop 0
	global_load_lds_dwordx4 v[224:225], off
	s_waitcnt vmcnt(8)
	s_waitcnt lgkmcnt(0)
	s_barrier
	s_setprio 1
	s_waitcnt lgkmcnt(0)
	v_mfma_f32_16x16x32_bf16 v[60:63], v[144:147], v[188:191], 0
	v_mfma_f32_16x16x32_bf16 v[56:59], v[160:163], v[188:191], 0
	v_mfma_f32_16x16x32_bf16 v[44:47], v[144:147], v[196:199], 0
	v_mfma_f32_16x16x32_bf16 v[40:43], v[160:163], v[196:199], 0
	v_mfma_f32_16x16x32_bf16 v[28:31], v[144:147], v[204:207], 0
	v_mfma_f32_16x16x32_bf16 v[24:27], v[160:163], v[204:207], 0
	v_mfma_f32_16x16x32_bf16 v[12:15], v[144:147], v[212:215], 0
	v_mfma_f32_16x16x32_bf16 v[8:11], v[160:163], v[212:215], 0
	v_mfma_f32_16x16x32_bf16 v[60:63], v[156:159], v[192:195], v[60:63]
	v_mfma_f32_16x16x32_bf16 v[56:59], v[164:167], v[192:195], v[56:59]
	v_mfma_f32_16x16x32_bf16 v[44:47], v[156:159], v[200:203], v[44:47]
	v_mfma_f32_16x16x32_bf16 v[40:43], v[164:167], v[200:203], v[40:43]
	v_mfma_f32_16x16x32_bf16 v[28:31], v[156:159], v[208:211], v[28:31]
	v_mfma_f32_16x16x32_bf16 v[24:27], v[164:167], v[208:211], v[24:27]
	v_mfma_f32_16x16x32_bf16 v[12:15], v[156:159], v[216:219], v[12:15]
	v_mfma_f32_16x16x32_bf16 v[8:11], v[164:167], v[216:219], v[8:11]
	s_setprio 0
	s_setprio 1
	v_mfma_f32_16x16x32_bf16 v[52:55], v[168:171], v[188:191], 0
	v_mfma_f32_16x16x32_bf16 v[48:51], v[180:183], v[188:191], 0
	v_mfma_f32_16x16x32_bf16 v[36:39], v[168:171], v[196:199], 0
	v_mfma_f32_16x16x32_bf16 v[32:35], v[180:183], v[196:199], 0
	v_mfma_f32_16x16x32_bf16 v[20:23], v[168:171], v[204:207], 0
	v_mfma_f32_16x16x32_bf16 v[16:19], v[180:183], v[204:207], 0
	v_mfma_f32_16x16x32_bf16 v[4:7], v[168:171], v[212:215], 0
	v_mfma_f32_16x16x32_bf16 v[0:3], v[180:183], v[212:215], 0
	v_mfma_f32_16x16x32_bf16 v[52:55], v[176:179], v[192:195], v[52:55]
	v_mfma_f32_16x16x32_bf16 v[48:51], v[184:187], v[192:195], v[48:51]
	v_mfma_f32_16x16x32_bf16 v[36:39], v[176:179], v[200:203], v[36:39]
	v_mfma_f32_16x16x32_bf16 v[32:35], v[184:187], v[200:203], v[32:35]
	v_mfma_f32_16x16x32_bf16 v[20:23], v[176:179], v[208:211], v[20:23]
	v_mfma_f32_16x16x32_bf16 v[16:19], v[184:187], v[208:211], v[16:19]
	v_mfma_f32_16x16x32_bf16 v[4:7], v[176:179], v[216:219], v[4:7]
	v_mfma_f32_16x16x32_bf16 v[0:3], v[184:187], v[216:219], v[0:3]
	s_setprio 0
	s_barrier
	s_add_i32 s52, 0, 0x18000
	v_add_u32_e32 v155, s52, v149
	s_add_i32 s53, 0, 0x1c000
	ds_read_b128 v[144:147], v155
	ds_read_b128 v[156:159], v155 offset:1024
	ds_read_b128 v[160:163], v155 offset:2048
	ds_read_b128 v[164:167], v155 offset:3072
	v_add_u32_e32 v155, s53, v149
	ds_read_b128 v[168:171], v155
	ds_read_b128 v[176:179], v155 offset:1024
	ds_read_b128 v[180:183], v155 offset:2048
	ds_read_b128 v[184:187], v155 offset:3072
	s_add_u32 s26, s34, 0xb0000
	s_addc_u32 s27, s35, 0
	s_mov_b32 m0, s36
	v_lshl_add_u64 v[226:227], s[26:27], 0, v[128:129]
	ds_read_b128 v[188:191], v153 offset:32768
	ds_read_b128 v[192:195], v153 offset:33792
	ds_read_b128 v[196:199], v153 offset:34816
	ds_read_b128 v[200:203], v153 offset:35840
	ds_read_b128 v[204:207], v153 offset:36864
	ds_read_b128 v[208:211], v153 offset:37888
	ds_read_b128 v[212:215], v153 offset:38912
	ds_read_b128 v[216:219], v153 offset:39936
	global_load_lds_dwordx4 v[226:227], off
	v_lshl_add_u64 v[226:227], s[26:27], 0, v[132:133]
	s_mov_b32 m0, s37
	s_nop 0
	global_load_lds_dwordx4 v[226:227], off
	s_waitcnt vmcnt(8)
	s_waitcnt lgkmcnt(0)
	s_barrier
	s_setprio 1
	s_waitcnt lgkmcnt(0)
	v_mfma_f32_16x16x32_bf16 v[124:127], v[144:147], v[188:191], v[124:127]
	v_mfma_f32_16x16x32_bf16 v[120:123], v[160:163], v[188:191], v[120:123]
	v_mfma_f32_16x16x32_bf16 v[108:111], v[144:147], v[196:199], v[108:111]
	v_mfma_f32_16x16x32_bf16 v[104:107], v[160:163], v[196:199], v[104:107]
	v_mfma_f32_16x16x32_bf16 v[92:95], v[144:147], v[204:207], v[92:95]
	v_mfma_f32_16x16x32_bf16 v[88:91], v[160:163], v[204:207], v[88:91]
	v_mfma_f32_16x16x32_bf16 v[76:79], v[144:147], v[212:215], v[76:79]
	v_mfma_f32_16x16x32_bf16 v[72:75], v[160:163], v[212:215], v[72:75]
	v_mfma_f32_16x16x32_bf16 v[124:127], v[156:159], v[192:195], v[124:127]
	v_mfma_f32_16x16x32_bf16 v[120:123], v[164:167], v[192:195], v[120:123]
	v_mfma_f32_16x16x32_bf16 v[108:111], v[156:159], v[200:203], v[108:111]
	v_mfma_f32_16x16x32_bf16 v[104:107], v[164:167], v[200:203], v[104:107]
	v_mfma_f32_16x16x32_bf16 v[92:95], v[156:159], v[208:211], v[92:95]
	v_mfma_f32_16x16x32_bf16 v[88:91], v[164:167], v[208:211], v[88:91]
	v_mfma_f32_16x16x32_bf16 v[76:79], v[156:159], v[216:219], v[76:79]
	v_mfma_f32_16x16x32_bf16 v[72:75], v[164:167], v[216:219], v[72:75]
	s_setprio 0
	s_setprio 1
	v_mfma_f32_16x16x32_bf16 v[116:119], v[168:171], v[188:191], v[116:119]
	v_mfma_f32_16x16x32_bf16 v[112:115], v[180:183], v[188:191], v[112:115]
	v_mfma_f32_16x16x32_bf16 v[100:103], v[168:171], v[196:199], v[100:103]
	v_mfma_f32_16x16x32_bf16 v[96:99], v[180:183], v[196:199], v[96:99]
	v_mfma_f32_16x16x32_bf16 v[84:87], v[168:171], v[204:207], v[84:87]
	v_mfma_f32_16x16x32_bf16 v[80:83], v[180:183], v[204:207], v[80:83]
	v_mfma_f32_16x16x32_bf16 v[68:71], v[168:171], v[212:215], v[68:71]
	v_mfma_f32_16x16x32_bf16 v[64:67], v[180:183], v[212:215], v[64:67]
	v_mfma_f32_16x16x32_bf16 v[116:119], v[176:179], v[192:195], v[116:119]
	v_mfma_f32_16x16x32_bf16 v[112:115], v[184:187], v[192:195], v[112:115]
	v_mfma_f32_16x16x32_bf16 v[100:103], v[176:179], v[200:203], v[100:103]
	v_mfma_f32_16x16x32_bf16 v[96:99], v[184:187], v[200:203], v[96:99]
	v_mfma_f32_16x16x32_bf16 v[84:87], v[176:179], v[208:211], v[84:87]
	v_mfma_f32_16x16x32_bf16 v[80:83], v[184:187], v[208:211], v[80:83]
	v_mfma_f32_16x16x32_bf16 v[68:71], v[176:179], v[216:219], v[68:71]
	v_mfma_f32_16x16x32_bf16 v[64:67], v[184:187], v[216:219], v[64:67]
	s_setprio 0
	s_barrier
	s_add_i32 s26, s52, s15
	v_lshl_add_u64 v[172:173], v[172:173], 0, s[20:21]
	s_mov_b32 m0, s26
	ds_read_b128 v[188:191], v153 offset:49152
	ds_read_b128 v[192:195], v153 offset:50176
	ds_read_b128 v[196:199], v153 offset:51200
	ds_read_b128 v[200:203], v153 offset:52224
	ds_read_b128 v[204:207], v153 offset:53248
	ds_read_b128 v[208:211], v153 offset:54272
	ds_read_b128 v[212:215], v153 offset:55296
	ds_read_b128 v[216:219], v153 offset:56320
	global_load_lds_dwordx4 v[172:173], off
	s_add_i32 m0, s26, 0x2000
	s_add_u32 s26, s30, 0xb0080
	v_lshl_add_u64 v[172:173], v[220:221], 0, s[20:21]
	s_addc_u32 s27, s31, 0
	s_add_i32 s30, s53, s15
	global_load_lds_dwordx4 v[172:173], off
	v_lshl_add_u64 v[172:173], s[26:27], 0, v[130:131]
	s_mov_b32 m0, s30
	s_nop 0
	global_load_lds_dwordx4 v[172:173], off
	v_lshl_add_u64 v[172:173], s[26:27], 0, v[134:135]
	s_add_i32 m0, s30, 0x2000
	s_nop 0
	global_load_lds_dwordx4 v[172:173], off
	v_lshl_add_u64 v[172:173], v[222:223], 0, s[20:21]
	s_mov_b32 m0, s39
	s_nop 0
	global_load_lds_dwordx4 v[172:173], off
	v_lshl_add_u64 v[172:173], v[224:225], 0, s[20:21]
	s_mov_b32 m0, s40
	s_nop 0
	global_load_lds_dwordx4 v[172:173], off
	s_waitcnt vmcnt(8)
	s_waitcnt lgkmcnt(0)
	s_barrier
	s_setprio 1
	s_waitcnt lgkmcnt(0)
	v_mfma_f32_16x16x32_bf16 v[60:63], v[144:147], v[188:191], v[60:63]
	v_mfma_f32_16x16x32_bf16 v[56:59], v[160:163], v[188:191], v[56:59]
	v_mfma_f32_16x16x32_bf16 v[44:47], v[144:147], v[196:199], v[44:47]
	v_mfma_f32_16x16x32_bf16 v[40:43], v[160:163], v[196:199], v[40:43]
	v_mfma_f32_16x16x32_bf16 v[28:31], v[144:147], v[204:207], v[28:31]
	v_mfma_f32_16x16x32_bf16 v[24:27], v[160:163], v[204:207], v[24:27]
	v_mfma_f32_16x16x32_bf16 v[12:15], v[144:147], v[212:215], v[12:15]
	v_mfma_f32_16x16x32_bf16 v[8:11], v[160:163], v[212:215], v[8:11]
	v_mfma_f32_16x16x32_bf16 v[60:63], v[156:159], v[192:195], v[60:63]
	v_mfma_f32_16x16x32_bf16 v[56:59], v[164:167], v[192:195], v[56:59]
	v_mfma_f32_16x16x32_bf16 v[44:47], v[156:159], v[200:203], v[44:47]
	v_mfma_f32_16x16x32_bf16 v[40:43], v[164:167], v[200:203], v[40:43]
	v_mfma_f32_16x16x32_bf16 v[28:31], v[156:159], v[208:211], v[28:31]
	v_mfma_f32_16x16x32_bf16 v[24:27], v[164:167], v[208:211], v[24:27]
	v_mfma_f32_16x16x32_bf16 v[12:15], v[156:159], v[216:219], v[12:15]
	v_mfma_f32_16x16x32_bf16 v[8:11], v[164:167], v[216:219], v[8:11]
	s_setprio 0
	s_setprio 1
	v_mfma_f32_16x16x32_bf16 v[52:55], v[168:171], v[188:191], v[52:55]
	v_mfma_f32_16x16x32_bf16 v[48:51], v[180:183], v[188:191], v[48:51]
	v_mfma_f32_16x16x32_bf16 v[36:39], v[168:171], v[196:199], v[36:39]
	v_mfma_f32_16x16x32_bf16 v[32:35], v[180:183], v[196:199], v[32:35]
	v_mfma_f32_16x16x32_bf16 v[20:23], v[168:171], v[204:207], v[20:23]
	v_mfma_f32_16x16x32_bf16 v[16:19], v[180:183], v[204:207], v[16:19]
	v_mfma_f32_16x16x32_bf16 v[4:7], v[168:171], v[212:215], v[4:7]
	v_mfma_f32_16x16x32_bf16 v[0:3], v[180:183], v[212:215], v[0:3]
	v_mfma_f32_16x16x32_bf16 v[52:55], v[176:179], v[192:195], v[52:55]
	v_mfma_f32_16x16x32_bf16 v[48:51], v[184:187], v[192:195], v[48:51]
	v_mfma_f32_16x16x32_bf16 v[36:39], v[176:179], v[200:203], v[36:39]
	v_mfma_f32_16x16x32_bf16 v[32:35], v[184:187], v[200:203], v[32:35]
	v_mfma_f32_16x16x32_bf16 v[20:23], v[176:179], v[208:211], v[20:23]
	v_mfma_f32_16x16x32_bf16 v[16:19], v[184:187], v[208:211], v[16:19]
	v_mfma_f32_16x16x32_bf16 v[4:7], v[176:179], v[216:219], v[4:7]
	v_mfma_f32_16x16x32_bf16 v[0:3], v[184:187], v[216:219], v[0:3]
	s_setprio 0
	s_barrier
	s_add_i32 s51, s51, 2
	s_add_u32 s49, s49, 0x100
	s_addc_u32 s50, s50, 0
	s_cmp_gt_u32 s51, 41
	s_mov_b64 s[26:27], s[28:29]
	s_cbranch_scc0 .LBB0_1684
	s_branch .Lpeel_exit_1684
